# conv: phase-start loads retired once before the unit loop; the per-unit wait in the FIR dropped so the next unit's prefetch stays in flight
# baseline (speedup 1.0000x reference)
.LBB0_438:
	s_lshl_b32 s0, s2, 7
	s_and_b32 s0, s0, 0x380
	s_ashr_i32 s4, s2, 3
	s_add_i32 s43, s0, s4
	s_add_i32 s0, 0, 0x10000
	v_lshl_add_u32 v35, v65, 2, s0
	v_mbcnt_hi_u32_b32 v65, -1, v243
	v_and_b32_e32 v101, 64, v65
	v_add_u32_e32 v106, 64, v101
	v_xor_b32_e32 v101, 1, v65
	v_cmp_lt_i32_e32 vcc, v101, v106
	v_xor_b32_e32 v102, 2, v65
	v_xor_b32_e32 v103, 4, v65
	v_cndmask_b32_e32 v101, v65, v101, vcc
	v_cmp_lt_i32_e32 vcc, v102, v106
	v_xor_b32_e32 v104, 8, v65
	v_xor_b32_e32 v105, 16, v65
	v_cndmask_b32_e32 v102, v65, v102, vcc
	v_cmp_lt_i32_e32 vcc, v103, v106
	v_xor_b32_e32 v107, 32, v65
	v_add_u32_e32 v33, 0, v62
	v_cndmask_b32_e32 v103, v65, v103, vcc
	v_cmp_lt_i32_e32 vcc, v104, v106
	v_and_b32_e32 v55, 0x7ffffe00, v55
	v_lshl_add_u32 v100, v172, 2, s0
	v_cndmask_b32_e32 v104, v65, v104, vcc
	v_cmp_lt_i32_e32 vcc, v105, v106
	s_movk_i32 s0, 0xf80
	v_mov_b32_e32 v32, 0
	v_cndmask_b32_e32 v105, v65, v105, vcc
	v_cmp_lt_i32_e32 vcc, v107, v106
	v_cmp_gt_i32_e64 s[4:5], s0, v172
	s_movk_i32 s0, 0xd80
	v_cndmask_b32_e32 v65, v65, v107, vcc
	v_lshl_add_u32 v107, v55, 1, v33
	v_lshlrev_b32_e32 v55, 4, v56
	v_and_b32_e32 v55, 0xfffffc00, v55
	v_add_u32_e32 v108, v33, v55
	v_lshlrev_b32_e32 v55, 4, v57
	v_and_b32_e32 v55, 0xfffffc00, v55
	v_add_u32_e32 v109, v33, v55
	v_lshlrev_b32_e32 v55, 4, v58
	v_and_b32_e32 v55, 0xfffffc00, v55
	v_add_u32_e32 v110, v33, v55
	v_lshlrev_b32_e32 v55, 4, v59
	v_and_b32_e32 v55, 0xfffffc00, v55
	v_add_u32_e32 v111, v33, v55
	v_lshlrev_b32_e32 v55, 4, v60
	v_and_b32_e32 v55, 0xfffffc00, v55
	v_mov_b32_e32 v63, v32
	v_cmp_gt_i32_e64 s[6:7], s0, v172
	s_movk_i32 s0, 0xb80
	v_add_u32_e32 v112, v33, v55
	v_lshlrev_b32_e32 v55, 4, v61
	v_lshl_add_u64 v[52:53], s[8:9], 0, v[62:63]
	v_ashrrev_i32_e32 v34, 4, v172
	v_cmp_gt_i32_e64 s[8:9], s0, v172
	s_movk_i32 s0, 0x980
	v_and_b32_e32 v55, 0xfffffc00, v55
	v_and_b32_e32 v54, -4, v34
	v_cmp_gt_i32_e64 s[10:11], s0, v172
	s_movk_i32 s0, 0x780
	v_add_u32_e32 v113, v33, v55
	v_lshlrev_b32_e32 v55, 4, v64
	v_cmp_gt_i32_e64 s[12:13], s0, v172
	s_movk_i32 s0, 0x580
	v_and_b32_e32 v55, 0xfffffc00, v55
	v_ashrrev_i32_e32 v115, 6, v56
	v_ashrrev_i32_e32 v117, 6, v58
	v_ashrrev_i32_e32 v119, 6, v60
	v_or_b32_e32 v56, 1, v54
	v_or_b32_e32 v58, 2, v54
	v_or_b32_e32 v60, 3, v34
	s_movk_i32 s1, 0x380
	v_lshlrev_b32_e32 v106, 2, v65
	v_cmp_gt_i32_e64 s[14:15], s0, v172
	s_movk_i32 s0, 0x180
	v_add_u32_e32 v114, v33, v55
	v_ashrrev_i32_e32 v121, 6, v64
	v_lshlrev_b32_e32 v33, 11, v54
	v_lshlrev_b32_e32 v64, 11, v56
	v_lshlrev_b32_e32 v65, 11, v58
	v_lshlrev_b32_e32 v34, 11, v60
	s_mov_b32 s44, 0
	v_lshl_add_u32 v99, v172, 1, 0
	v_lshlrev_b32_e32 v101, 2, v101
	v_lshlrev_b32_e32 v102, 2, v102
	v_lshlrev_b32_e32 v103, 2, v103
	v_lshlrev_b32_e32 v104, 2, v104
	v_lshlrev_b32_e32 v105, 2, v105
	v_cmp_gt_i32_e64 s[16:17], s1, v172
	v_cmp_gt_i32_e64 s[18:19], s0, v172
	v_ashrrev_i32_e32 v116, 6, v57
	v_ashrrev_i32_e32 v118, 6, v59
	v_ashrrev_i32_e32 v120, 6, v61
	v_ashrrev_i32_e32 v55, 31, v54
	v_ashrrev_i32_e32 v57, 31, v56
	v_ashrrev_i32_e32 v59, 31, v58
	v_ashrrev_i32_e32 v61, 31, v60
	v_lshl_add_u64 v[62:63], s[36:37], 0, v[62:63]
	v_add_u32_e32 v122, v35, v33
	v_mov_b32_e32 v123, 0x358637bd
	s_mov_b32 s45, 0xf800000
	v_mov_b32_e32 v124, 0x260
	s_movk_i32 s52, 0x7fff
	s_mov_b32 s53, 0xffff0000
	v_add_u32_e32 v125, v35, v64
	v_add_u32_e32 v126, v35, v65
	v_add_u32_e32 v127, v35, v34
	s_waitcnt vmcnt(0)
	s_branch .LBB0_441

.LBB0_440:
	ds_read_u16 v128, v99
	ds_read_u16 v129, v99 offset:1024
	ds_read_u16 v130, v99 offset:2048
	ds_read_u16 v131, v99 offset:3072
	ds_read_u16 v132, v99 offset:4096
	ds_read_u16 v133, v99 offset:5120
	ds_read_u16 v134, v99 offset:6144
	ds_read_u16 v135, v99 offset:7168
	ds_read_u16 v136, v99 offset:8192
	ds_read_u16 v137, v99 offset:9216
	ds_read_u16 v138, v99 offset:10240
	ds_read_u16 v139, v99 offset:11264
	ds_read_u16 v140, v99 offset:12288
	ds_read_u16 v141, v99 offset:13312
	s_waitcnt lgkmcnt(7)
	v_lshlrev_b32_e32 v128, 16, v128
	v_lshlrev_b32_e32 v129, 16, v129
	v_lshlrev_b32_e32 v130, 16, v130
	v_lshlrev_b32_e32 v131, 16, v131
	v_lshlrev_b32_e32 v132, 16, v132
	v_lshlrev_b32_e32 v133, 16, v133
	v_lshlrev_b32_e32 v134, 16, v134
	ds_read_u16 v142, v99 offset:14336
	ds_read_u16 v143, v99 offset:15360
	ds_read_u16 v144, v99 offset:16384
	ds_read_u16 v145, v99 offset:17408
	ds_read_u16 v146, v99 offset:18432
	ds_read_u16 v147, v99 offset:19456
	ds_read_u16 v148, v99 offset:20480
	s_waitcnt lgkmcnt(7)
	v_lshlrev_b32_e32 v135, 16, v135
	v_lshlrev_b32_e32 v136, 16, v136
	v_lshlrev_b32_e32 v137, 16, v137
	v_lshlrev_b32_e32 v138, 16, v138
	v_lshlrev_b32_e32 v139, 16, v139
	v_lshlrev_b32_e32 v140, 16, v140
	v_lshlrev_b32_e32 v141, 16, v141
	ds_read_u16 v149, v99 offset:21504
	ds_read_u16 v150, v99 offset:22528
	ds_read_u16 v151, v99 offset:23552
	ds_read_u16 v152, v99 offset:24576
	ds_read_u16 v153, v99 offset:25600
	ds_read_u16 v154, v99 offset:26624
	ds_read_u16 v155, v99 offset:27648
	s_waitcnt lgkmcnt(7)
	v_lshlrev_b32_e32 v142, 16, v142
	v_lshlrev_b32_e32 v143, 16, v143
	v_lshlrev_b32_e32 v144, 16, v144
	v_lshlrev_b32_e32 v145, 16, v145
	v_lshlrev_b32_e32 v146, 16, v146
	v_lshlrev_b32_e32 v147, 16, v147
	v_lshlrev_b32_e32 v148, 16, v148
	ds_read_u16 v156, v99 offset:28672
	ds_read_u16 v157, v99 offset:29696
	ds_read_u16 v158, v99 offset:30720
	ds_read_u16 v159, v99 offset:31744
	ds_read_u16 v160, v99 offset:32768
	ds_read_u16 v161, v99 offset:33792
	ds_read_u16 v162, v99 offset:34816
	s_waitcnt lgkmcnt(7)
	v_lshlrev_b32_e32 v149, 16, v149
	v_lshlrev_b32_e32 v150, 16, v150
	v_lshlrev_b32_e32 v151, 16, v151
	v_lshlrev_b32_e32 v152, 16, v152
	v_lshlrev_b32_e32 v153, 16, v153
	v_lshlrev_b32_e32 v154, 16, v154
	v_lshlrev_b32_e32 v155, 16, v155
	ds_read_u16 v163, v99 offset:35840
	ds_read_u16 v164, v99 offset:36864
	ds_read_u16 v165, v99 offset:37888
	ds_read_u16 v166, v99 offset:38912
	ds_read_u16 v167, v99 offset:39936
	ds_read_u16 v168, v99 offset:40960
	ds_read_u16 v169, v99 offset:41984
	s_waitcnt lgkmcnt(7)
	v_lshlrev_b32_e32 v156, 16, v156
	v_lshlrev_b32_e32 v157, 16, v157
	v_lshlrev_b32_e32 v158, 16, v158
	v_lshlrev_b32_e32 v159, 16, v159
	v_lshlrev_b32_e32 v160, 16, v160
	v_lshlrev_b32_e32 v161, 16, v161
	v_lshlrev_b32_e32 v162, 16, v162
	ds_read_u16 v170, v99 offset:43008
	ds_read_u16 v171, v99 offset:44032
	ds_read_u16 v174, v99 offset:45056
	ds_read_u16 v175, v99 offset:46080
	ds_read_u16 v176, v99 offset:47104
	ds_read_u16 v177, v99 offset:48128
	ds_read_u16 v178, v99 offset:49152
	s_waitcnt lgkmcnt(7)
	v_lshlrev_b32_e32 v163, 16, v163
	v_lshlrev_b32_e32 v164, 16, v164
	v_lshlrev_b32_e32 v165, 16, v165
	v_lshlrev_b32_e32 v166, 16, v166
	v_lshlrev_b32_e32 v167, 16, v167
	v_lshlrev_b32_e32 v168, 16, v168
	v_lshlrev_b32_e32 v169, 16, v169
	ds_read_u16 v179, v99 offset:50176
	ds_read_u16 v180, v99 offset:51200
	ds_read_u16 v181, v99 offset:52224
	ds_read_u16 v182, v99 offset:53248
	ds_read_u16 v183, v99 offset:54272
	ds_read_u16 v184, v99 offset:55296
	ds_read_u16 v185, v99 offset:56320
	s_waitcnt lgkmcnt(7)
	v_lshlrev_b32_e32 v170, 16, v170
	v_lshlrev_b32_e32 v171, 16, v171
	v_lshlrev_b32_e32 v174, 16, v174
	v_lshlrev_b32_e32 v175, 16, v175
	v_lshlrev_b32_e32 v176, 16, v176
	v_lshlrev_b32_e32 v177, 16, v177
	v_lshlrev_b32_e32 v178, 16, v178
	ds_read_u16 v186, v99 offset:57344
	ds_read_u16 v187, v99 offset:58368
	ds_read_u16 v188, v99 offset:59392
	ds_read_u16 v189, v99 offset:60416
	ds_read_u16 v190, v99 offset:61440
	ds_read_u16 v191, v99 offset:62464
	s_waitcnt lgkmcnt(6)
	v_lshlrev_b32_e32 v179, 16, v179
	v_lshlrev_b32_e32 v180, 16, v180
	v_lshlrev_b32_e32 v181, 16, v181
	v_lshlrev_b32_e32 v182, 16, v182
	v_lshlrev_b32_e32 v183, 16, v183
	v_lshlrev_b32_e32 v184, 16, v184
	v_lshlrev_b32_e32 v185, 16, v185
	s_waitcnt lgkmcnt(0)
	v_lshlrev_b32_e32 v186, 16, v186
	v_lshlrev_b32_e32 v187, 16, v187
	v_lshlrev_b32_e32 v188, 16, v188
	v_lshlrev_b32_e32 v189, 16, v189
	v_lshlrev_b32_e32 v190, 16, v190
	v_lshlrev_b32_e32 v191, 16, v191
	v_mov_b32_e32 v200, v67
	v_mov_b32_e32 v201, v68
	v_mov_b32_e32 v202, v69
	v_mov_b32_e32 v203, v70
	v_mov_b32_e32 v204, v71
	v_mov_b32_e32 v205, v72
	v_mov_b32_e32 v206, v73
	v_mov_b32_e32 v207, v74
	v_mov_b32_e32 v208, v75
	v_mov_b32_e32 v209, v76
	v_mov_b32_e32 v210, v77
	v_mov_b32_e32 v211, v78
	v_mov_b32_e32 v212, v79
	v_mov_b32_e32 v213, v80
	v_mov_b32_e32 v214, v81
	v_mov_b32_e32 v215, v82
	v_mov_b32_e32 v216, v83
	v_mov_b32_e32 v217, v84
	v_mov_b32_e32 v218, v85
	v_mov_b32_e32 v219, v86
	v_mov_b32_e32 v220, v87
	v_mov_b32_e32 v221, v88
	v_mov_b32_e32 v222, v89
	v_mov_b32_e32 v223, v90
	v_mov_b32_e32 v224, v91
	v_mov_b32_e32 v225, v92
	v_mov_b32_e32 v226, v93
	v_mov_b32_e32 v227, v94
	v_mov_b32_e32 v228, v95
	v_mov_b32_e32 v229, v96
	v_mov_b32_e32 v230, v97
	v_mov_b32_e32 v231, 0
	v_pk_fma_f32 v[192:193], v[66:67], v[128:129], v[230:231]
	v_pk_fma_f32 v[192:193], v[68:69], v[130:131], v[192:193]
	v_pk_fma_f32 v[192:193], v[70:71], v[132:133], v[192:193]
	v_pk_fma_f32 v[192:193], v[72:73], v[134:135], v[192:193]
	v_pk_fma_f32 v[192:193], v[74:75], v[136:137], v[192:193]
	v_pk_fma_f32 v[192:193], v[76:77], v[138:139], v[192:193]
	v_pk_fma_f32 v[192:193], v[78:79], v[140:141], v[192:193]
	v_pk_fma_f32 v[192:193], v[80:81], v[142:143], v[192:193]
	v_pk_fma_f32 v[192:193], v[82:83], v[144:145], v[192:193]
	v_pk_fma_f32 v[192:193], v[84:85], v[146:147], v[192:193]
	v_pk_fma_f32 v[192:193], v[86:87], v[148:149], v[192:193]
	v_pk_fma_f32 v[192:193], v[88:89], v[150:151], v[192:193]
	v_pk_fma_f32 v[192:193], v[90:91], v[152:153], v[192:193]
	v_pk_fma_f32 v[192:193], v[92:93], v[154:155], v[192:193]
	v_pk_fma_f32 v[192:193], v[94:95], v[156:157], v[192:193]
	v_fmac_f32_e32 v192, v96, v158
	v_add_f32_e32 v232, v193, v192
	v_fma_f32 v195, v66, v129, v97
	v_mov_b32_e32 v194, 0
	v_pk_fma_f32 v[194:195], v[200:201], v[130:131], v[194:195]
	v_pk_fma_f32 v[194:195], v[202:203], v[132:133], v[194:195]
	v_pk_fma_f32 v[194:195], v[204:205], v[134:135], v[194:195]
	v_pk_fma_f32 v[194:195], v[206:207], v[136:137], v[194:195]
	v_pk_fma_f32 v[194:195], v[208:209], v[138:139], v[194:195]
	v_pk_fma_f32 v[194:195], v[210:211], v[140:141], v[194:195]
	v_pk_fma_f32 v[194:195], v[212:213], v[142:143], v[194:195]
	v_pk_fma_f32 v[194:195], v[214:215], v[144:145], v[194:195]
	v_pk_fma_f32 v[194:195], v[216:217], v[146:147], v[194:195]
	v_pk_fma_f32 v[194:195], v[218:219], v[148:149], v[194:195]
	v_pk_fma_f32 v[194:195], v[220:221], v[150:151], v[194:195]
	v_pk_fma_f32 v[194:195], v[222:223], v[152:153], v[194:195]
	v_pk_fma_f32 v[194:195], v[224:225], v[154:155], v[194:195]
	v_pk_fma_f32 v[194:195], v[226:227], v[156:157], v[194:195]
	v_pk_fma_f32 v[194:195], v[228:229], v[158:159], v[194:195]
	v_add_f32_e32 v233, v194, v195
	ds_write2st64_b32 v100, v232, v233 offset1:8
	v_pk_fma_f32 v[196:197], v[66:67], v[130:131], v[230:231]
	v_pk_fma_f32 v[196:197], v[68:69], v[132:133], v[196:197]
	v_pk_fma_f32 v[196:197], v[70:71], v[134:135], v[196:197]
	v_pk_fma_f32 v[196:197], v[72:73], v[136:137], v[196:197]
	v_pk_fma_f32 v[196:197], v[74:75], v[138:139], v[196:197]
	v_pk_fma_f32 v[196:197], v[76:77], v[140:141], v[196:197]
	v_pk_fma_f32 v[196:197], v[78:79], v[142:143], v[196:197]
	v_pk_fma_f32 v[196:197], v[80:81], v[144:145], v[196:197]
	v_pk_fma_f32 v[196:197], v[82:83], v[146:147], v[196:197]
	v_pk_fma_f32 v[196:197], v[84:85], v[148:149], v[196:197]
	v_pk_fma_f32 v[196:197], v[86:87], v[150:151], v[196:197]
	v_pk_fma_f32 v[196:197], v[88:89], v[152:153], v[196:197]
	v_pk_fma_f32 v[196:197], v[90:91], v[154:155], v[196:197]
	v_pk_fma_f32 v[196:197], v[92:93], v[156:157], v[196:197]
	v_pk_fma_f32 v[196:197], v[94:95], v[158:159], v[196:197]
	v_fmac_f32_e32 v196, v96, v160
	v_add_f32_e32 v234, v197, v196
	v_fma_f32 v199, v66, v131, v97
	v_mov_b32_e32 v198, 0
	v_pk_fma_f32 v[198:199], v[200:201], v[132:133], v[198:199]
	v_pk_fma_f32 v[198:199], v[202:203], v[134:135], v[198:199]
	v_pk_fma_f32 v[198:199], v[204:205], v[136:137], v[198:199]
	v_pk_fma_f32 v[198:199], v[206:207], v[138:139], v[198:199]
	v_pk_fma_f32 v[198:199], v[208:209], v[140:141], v[198:199]
	v_pk_fma_f32 v[198:199], v[210:211], v[142:143], v[198:199]
	v_pk_fma_f32 v[198:199], v[212:213], v[144:145], v[198:199]
	v_pk_fma_f32 v[198:199], v[214:215], v[146:147], v[198:199]
	v_pk_fma_f32 v[198:199], v[216:217], v[148:149], v[198:199]
	v_pk_fma_f32 v[198:199], v[218:219], v[150:151], v[198:199]
	v_pk_fma_f32 v[198:199], v[220:221], v[152:153], v[198:199]
	v_pk_fma_f32 v[198:199], v[222:223], v[154:155], v[198:199]
	v_pk_fma_f32 v[198:199], v[224:225], v[156:157], v[198:199]
	v_pk_fma_f32 v[198:199], v[226:227], v[158:159], v[198:199]
	v_pk_fma_f32 v[198:199], v[228:229], v[160:161], v[198:199]
	v_add_f32_e32 v235, v198, v199
	ds_write2st64_b32 v100, v234, v235 offset0:16 offset1:24
	v_pk_fma_f32 v[192:193], v[66:67], v[132:133], v[230:231]
	v_pk_fma_f32 v[192:193], v[68:69], v[134:135], v[192:193]
	v_pk_fma_f32 v[192:193], v[70:71], v[136:137], v[192:193]
	v_pk_fma_f32 v[192:193], v[72:73], v[138:139], v[192:193]
	v_pk_fma_f32 v[192:193], v[74:75], v[140:141], v[192:193]
	v_pk_fma_f32 v[192:193], v[76:77], v[142:143], v[192:193]
	v_pk_fma_f32 v[192:193], v[78:79], v[144:145], v[192:193]
	v_pk_fma_f32 v[192:193], v[80:81], v[146:147], v[192:193]
	v_pk_fma_f32 v[192:193], v[82:83], v[148:149], v[192:193]
	v_pk_fma_f32 v[192:193], v[84:85], v[150:151], v[192:193]
	v_pk_fma_f32 v[192:193], v[86:87], v[152:153], v[192:193]
	v_pk_fma_f32 v[192:193], v[88:89], v[154:155], v[192:193]
	v_pk_fma_f32 v[192:193], v[90:91], v[156:157], v[192:193]
	v_pk_fma_f32 v[192:193], v[92:93], v[158:159], v[192:193]
	v_pk_fma_f32 v[192:193], v[94:95], v[160:161], v[192:193]
	v_fmac_f32_e32 v192, v96, v162
	v_add_f32_e32 v232, v193, v192
	v_fma_f32 v195, v66, v133, v97
	v_mov_b32_e32 v194, 0
	v_pk_fma_f32 v[194:195], v[200:201], v[134:135], v[194:195]
	v_pk_fma_f32 v[194:195], v[202:203], v[136:137], v[194:195]
	v_pk_fma_f32 v[194:195], v[204:205], v[138:139], v[194:195]
	v_pk_fma_f32 v[194:195], v[206:207], v[140:141], v[194:195]
	v_pk_fma_f32 v[194:195], v[208:209], v[142:143], v[194:195]
	v_pk_fma_f32 v[194:195], v[210:211], v[144:145], v[194:195]
	v_pk_fma_f32 v[194:195], v[212:213], v[146:147], v[194:195]
	v_pk_fma_f32 v[194:195], v[214:215], v[148:149], v[194:195]
	v_pk_fma_f32 v[194:195], v[216:217], v[150:151], v[194:195]
	v_pk_fma_f32 v[194:195], v[218:219], v[152:153], v[194:195]
	v_pk_fma_f32 v[194:195], v[220:221], v[154:155], v[194:195]
	v_pk_fma_f32 v[194:195], v[222:223], v[156:157], v[194:195]
	v_pk_fma_f32 v[194:195], v[224:225], v[158:159], v[194:195]
	v_pk_fma_f32 v[194:195], v[226:227], v[160:161], v[194:195]
	v_pk_fma_f32 v[194:195], v[228:229], v[162:163], v[194:195]
	v_add_f32_e32 v233, v194, v195
	ds_write2st64_b32 v100, v232, v233 offset0:32 offset1:40
	v_pk_fma_f32 v[196:197], v[66:67], v[134:135], v[230:231]
	v_pk_fma_f32 v[196:197], v[68:69], v[136:137], v[196:197]
	v_pk_fma_f32 v[196:197], v[70:71], v[138:139], v[196:197]
	v_pk_fma_f32 v[196:197], v[72:73], v[140:141], v[196:197]
	v_pk_fma_f32 v[196:197], v[74:75], v[142:143], v[196:197]
	v_pk_fma_f32 v[196:197], v[76:77], v[144:145], v[196:197]
	v_pk_fma_f32 v[196:197], v[78:79], v[146:147], v[196:197]
	v_pk_fma_f32 v[196:197], v[80:81], v[148:149], v[196:197]
	v_pk_fma_f32 v[196:197], v[82:83], v[150:151], v[196:197]
	v_pk_fma_f32 v[196:197], v[84:85], v[152:153], v[196:197]
	v_pk_fma_f32 v[196:197], v[86:87], v[154:155], v[196:197]
	v_pk_fma_f32 v[196:197], v[88:89], v[156:157], v[196:197]
	v_pk_fma_f32 v[196:197], v[90:91], v[158:159], v[196:197]
	v_pk_fma_f32 v[196:197], v[92:93], v[160:161], v[196:197]
	v_pk_fma_f32 v[196:197], v[94:95], v[162:163], v[196:197]
	v_fmac_f32_e32 v196, v96, v164
	v_add_f32_e32 v234, v197, v196
	v_fma_f32 v199, v66, v135, v97
	v_mov_b32_e32 v198, 0
	v_pk_fma_f32 v[198:199], v[200:201], v[136:137], v[198:199]
	v_pk_fma_f32 v[198:199], v[202:203], v[138:139], v[198:199]
	v_pk_fma_f32 v[198:199], v[204:205], v[140:141], v[198:199]
	v_pk_fma_f32 v[198:199], v[206:207], v[142:143], v[198:199]
	v_pk_fma_f32 v[198:199], v[208:209], v[144:145], v[198:199]
	v_pk_fma_f32 v[198:199], v[210:211], v[146:147], v[198:199]
	v_pk_fma_f32 v[198:199], v[212:213], v[148:149], v[198:199]
	v_pk_fma_f32 v[198:199], v[214:215], v[150:151], v[198:199]
	v_pk_fma_f32 v[198:199], v[216:217], v[152:153], v[198:199]
	v_pk_fma_f32 v[198:199], v[218:219], v[154:155], v[198:199]
	v_pk_fma_f32 v[198:199], v[220:221], v[156:157], v[198:199]
	v_pk_fma_f32 v[198:199], v[222:223], v[158:159], v[198:199]
	v_pk_fma_f32 v[198:199], v[224:225], v[160:161], v[198:199]
	v_pk_fma_f32 v[198:199], v[226:227], v[162:163], v[198:199]
	v_pk_fma_f32 v[198:199], v[228:229], v[164:165], v[198:199]
	v_add_f32_e32 v235, v198, v199
	ds_write2st64_b32 v100, v234, v235 offset0:48 offset1:56
	v_pk_fma_f32 v[192:193], v[66:67], v[136:137], v[230:231]
	v_pk_fma_f32 v[192:193], v[68:69], v[138:139], v[192:193]
	v_pk_fma_f32 v[192:193], v[70:71], v[140:141], v[192:193]
	v_pk_fma_f32 v[192:193], v[72:73], v[142:143], v[192:193]
	v_pk_fma_f32 v[192:193], v[74:75], v[144:145], v[192:193]
	v_pk_fma_f32 v[192:193], v[76:77], v[146:147], v[192:193]
	v_pk_fma_f32 v[192:193], v[78:79], v[148:149], v[192:193]
	v_pk_fma_f32 v[192:193], v[80:81], v[150:151], v[192:193]
	v_pk_fma_f32 v[192:193], v[82:83], v[152:153], v[192:193]
	v_pk_fma_f32 v[192:193], v[84:85], v[154:155], v[192:193]
	v_pk_fma_f32 v[192:193], v[86:87], v[156:157], v[192:193]
	v_pk_fma_f32 v[192:193], v[88:89], v[158:159], v[192:193]
	v_pk_fma_f32 v[192:193], v[90:91], v[160:161], v[192:193]
	v_pk_fma_f32 v[192:193], v[92:93], v[162:163], v[192:193]
	v_pk_fma_f32 v[192:193], v[94:95], v[164:165], v[192:193]
	v_fmac_f32_e32 v192, v96, v166
	v_add_f32_e32 v232, v193, v192
	v_fma_f32 v195, v66, v137, v97
	v_mov_b32_e32 v194, 0
	v_pk_fma_f32 v[194:195], v[200:201], v[138:139], v[194:195]
	v_pk_fma_f32 v[194:195], v[202:203], v[140:141], v[194:195]
	v_pk_fma_f32 v[194:195], v[204:205], v[142:143], v[194:195]
	v_pk_fma_f32 v[194:195], v[206:207], v[144:145], v[194:195]
	v_pk_fma_f32 v[194:195], v[208:209], v[146:147], v[194:195]
	v_pk_fma_f32 v[194:195], v[210:211], v[148:149], v[194:195]
	v_pk_fma_f32 v[194:195], v[212:213], v[150:151], v[194:195]
	v_pk_fma_f32 v[194:195], v[214:215], v[152:153], v[194:195]
	v_pk_fma_f32 v[194:195], v[216:217], v[154:155], v[194:195]
	v_pk_fma_f32 v[194:195], v[218:219], v[156:157], v[194:195]
	v_pk_fma_f32 v[194:195], v[220:221], v[158:159], v[194:195]
	v_pk_fma_f32 v[194:195], v[222:223], v[160:161], v[194:195]
	v_pk_fma_f32 v[194:195], v[224:225], v[162:163], v[194:195]
	v_pk_fma_f32 v[194:195], v[226:227], v[164:165], v[194:195]
	v_pk_fma_f32 v[194:195], v[228:229], v[166:167], v[194:195]
	v_add_f32_e32 v233, v194, v195
	ds_write2st64_b32 v100, v232, v233 offset0:64 offset1:72
	v_pk_fma_f32 v[196:197], v[66:67], v[138:139], v[230:231]
	v_pk_fma_f32 v[196:197], v[68:69], v[140:141], v[196:197]
	v_pk_fma_f32 v[196:197], v[70:71], v[142:143], v[196:197]
	v_pk_fma_f32 v[196:197], v[72:73], v[144:145], v[196:197]
	v_pk_fma_f32 v[196:197], v[74:75], v[146:147], v[196:197]
	v_pk_fma_f32 v[196:197], v[76:77], v[148:149], v[196:197]
	v_pk_fma_f32 v[196:197], v[78:79], v[150:151], v[196:197]
	v_pk_fma_f32 v[196:197], v[80:81], v[152:153], v[196:197]
	v_pk_fma_f32 v[196:197], v[82:83], v[154:155], v[196:197]
	v_pk_fma_f32 v[196:197], v[84:85], v[156:157], v[196:197]
	v_pk_fma_f32 v[196:197], v[86:87], v[158:159], v[196:197]
	v_pk_fma_f32 v[196:197], v[88:89], v[160:161], v[196:197]
	v_pk_fma_f32 v[196:197], v[90:91], v[162:163], v[196:197]
	v_pk_fma_f32 v[196:197], v[92:93], v[164:165], v[196:197]
	v_pk_fma_f32 v[196:197], v[94:95], v[166:167], v[196:197]
	v_fmac_f32_e32 v196, v96, v168
	v_add_f32_e32 v234, v197, v196
	v_fma_f32 v199, v66, v139, v97
	v_mov_b32_e32 v198, 0
	v_pk_fma_f32 v[198:199], v[200:201], v[140:141], v[198:199]
	v_pk_fma_f32 v[198:199], v[202:203], v[142:143], v[198:199]
	v_pk_fma_f32 v[198:199], v[204:205], v[144:145], v[198:199]
	v_pk_fma_f32 v[198:199], v[206:207], v[146:147], v[198:199]
	v_pk_fma_f32 v[198:199], v[208:209], v[148:149], v[198:199]
	v_pk_fma_f32 v[198:199], v[210:211], v[150:151], v[198:199]
	v_pk_fma_f32 v[198:199], v[212:213], v[152:153], v[198:199]
	v_pk_fma_f32 v[198:199], v[214:215], v[154:155], v[198:199]
	v_pk_fma_f32 v[198:199], v[216:217], v[156:157], v[198:199]
	v_pk_fma_f32 v[198:199], v[218:219], v[158:159], v[198:199]
	v_pk_fma_f32 v[198:199], v[220:221], v[160:161], v[198:199]
	v_pk_fma_f32 v[198:199], v[222:223], v[162:163], v[198:199]
	v_pk_fma_f32 v[198:199], v[224:225], v[164:165], v[198:199]
	v_pk_fma_f32 v[198:199], v[226:227], v[166:167], v[198:199]
	v_pk_fma_f32 v[198:199], v[228:229], v[168:169], v[198:199]
	v_add_f32_e32 v235, v198, v199
	ds_write2st64_b32 v100, v234, v235 offset0:80 offset1:88
	v_pk_fma_f32 v[192:193], v[66:67], v[140:141], v[230:231]
	v_pk_fma_f32 v[192:193], v[68:69], v[142:143], v[192:193]
	v_pk_fma_f32 v[192:193], v[70:71], v[144:145], v[192:193]
	v_pk_fma_f32 v[192:193], v[72:73], v[146:147], v[192:193]
	v_pk_fma_f32 v[192:193], v[74:75], v[148:149], v[192:193]
	v_pk_fma_f32 v[192:193], v[76:77], v[150:151], v[192:193]
	v_pk_fma_f32 v[192:193], v[78:79], v[152:153], v[192:193]
	v_pk_fma_f32 v[192:193], v[80:81], v[154:155], v[192:193]
	v_pk_fma_f32 v[192:193], v[82:83], v[156:157], v[192:193]
	v_pk_fma_f32 v[192:193], v[84:85], v[158:159], v[192:193]
	v_pk_fma_f32 v[192:193], v[86:87], v[160:161], v[192:193]
	v_pk_fma_f32 v[192:193], v[88:89], v[162:163], v[192:193]
	v_pk_fma_f32 v[192:193], v[90:91], v[164:165], v[192:193]
	v_pk_fma_f32 v[192:193], v[92:93], v[166:167], v[192:193]
	v_pk_fma_f32 v[192:193], v[94:95], v[168:169], v[192:193]
	v_fmac_f32_e32 v192, v96, v170
	v_add_f32_e32 v232, v193, v192
	v_fma_f32 v195, v66, v141, v97
	v_mov_b32_e32 v194, 0
	v_pk_fma_f32 v[194:195], v[200:201], v[142:143], v[194:195]
	v_pk_fma_f32 v[194:195], v[202:203], v[144:145], v[194:195]
	v_pk_fma_f32 v[194:195], v[204:205], v[146:147], v[194:195]
	v_pk_fma_f32 v[194:195], v[206:207], v[148:149], v[194:195]
	v_pk_fma_f32 v[194:195], v[208:209], v[150:151], v[194:195]
	v_pk_fma_f32 v[194:195], v[210:211], v[152:153], v[194:195]
	v_pk_fma_f32 v[194:195], v[212:213], v[154:155], v[194:195]
	v_pk_fma_f32 v[194:195], v[214:215], v[156:157], v[194:195]
	v_pk_fma_f32 v[194:195], v[216:217], v[158:159], v[194:195]
	v_pk_fma_f32 v[194:195], v[218:219], v[160:161], v[194:195]
	v_pk_fma_f32 v[194:195], v[220:221], v[162:163], v[194:195]
	v_pk_fma_f32 v[194:195], v[222:223], v[164:165], v[194:195]
	v_pk_fma_f32 v[194:195], v[224:225], v[166:167], v[194:195]
	v_pk_fma_f32 v[194:195], v[226:227], v[168:169], v[194:195]
	v_pk_fma_f32 v[194:195], v[228:229], v[170:171], v[194:195]
	v_add_f32_e32 v233, v194, v195
	ds_write2st64_b32 v100, v232, v233 offset0:96 offset1:104
	v_pk_fma_f32 v[196:197], v[66:67], v[142:143], v[230:231]
	v_pk_fma_f32 v[196:197], v[68:69], v[144:145], v[196:197]
	v_pk_fma_f32 v[196:197], v[70:71], v[146:147], v[196:197]
	v_pk_fma_f32 v[196:197], v[72:73], v[148:149], v[196:197]
	v_pk_fma_f32 v[196:197], v[74:75], v[150:151], v[196:197]
	v_pk_fma_f32 v[196:197], v[76:77], v[152:153], v[196:197]
	v_pk_fma_f32 v[196:197], v[78:79], v[154:155], v[196:197]
	v_pk_fma_f32 v[196:197], v[80:81], v[156:157], v[196:197]
	v_pk_fma_f32 v[196:197], v[82:83], v[158:159], v[196:197]
	v_pk_fma_f32 v[196:197], v[84:85], v[160:161], v[196:197]
	v_pk_fma_f32 v[196:197], v[86:87], v[162:163], v[196:197]
	v_pk_fma_f32 v[196:197], v[88:89], v[164:165], v[196:197]
	v_pk_fma_f32 v[196:197], v[90:91], v[166:167], v[196:197]
	v_pk_fma_f32 v[196:197], v[92:93], v[168:169], v[196:197]
	v_pk_fma_f32 v[196:197], v[94:95], v[170:171], v[196:197]
	v_fmac_f32_e32 v196, v96, v174
	v_add_f32_e32 v234, v197, v196
	v_fma_f32 v199, v66, v143, v97
	v_mov_b32_e32 v198, 0
	v_pk_fma_f32 v[198:199], v[200:201], v[144:145], v[198:199]
	v_pk_fma_f32 v[198:199], v[202:203], v[146:147], v[198:199]
	v_pk_fma_f32 v[198:199], v[204:205], v[148:149], v[198:199]
	v_pk_fma_f32 v[198:199], v[206:207], v[150:151], v[198:199]
	v_pk_fma_f32 v[198:199], v[208:209], v[152:153], v[198:199]
	v_pk_fma_f32 v[198:199], v[210:211], v[154:155], v[198:199]
	v_pk_fma_f32 v[198:199], v[212:213], v[156:157], v[198:199]
	v_pk_fma_f32 v[198:199], v[214:215], v[158:159], v[198:199]
	v_pk_fma_f32 v[198:199], v[216:217], v[160:161], v[198:199]
	v_pk_fma_f32 v[198:199], v[218:219], v[162:163], v[198:199]
	v_pk_fma_f32 v[198:199], v[220:221], v[164:165], v[198:199]
	v_pk_fma_f32 v[198:199], v[222:223], v[166:167], v[198:199]
	v_pk_fma_f32 v[198:199], v[224:225], v[168:169], v[198:199]
	v_pk_fma_f32 v[198:199], v[226:227], v[170:171], v[198:199]
	v_pk_fma_f32 v[198:199], v[228:229], v[174:175], v[198:199]
	v_add_f32_e32 v235, v198, v199
	ds_write2st64_b32 v100, v234, v235 offset0:112 offset1:120
	v_pk_fma_f32 v[192:193], v[66:67], v[144:145], v[230:231]
	v_pk_fma_f32 v[192:193], v[68:69], v[146:147], v[192:193]
	v_pk_fma_f32 v[192:193], v[70:71], v[148:149], v[192:193]
	v_pk_fma_f32 v[192:193], v[72:73], v[150:151], v[192:193]
	v_pk_fma_f32 v[192:193], v[74:75], v[152:153], v[192:193]
	v_pk_fma_f32 v[192:193], v[76:77], v[154:155], v[192:193]
	v_pk_fma_f32 v[192:193], v[78:79], v[156:157], v[192:193]
	v_pk_fma_f32 v[192:193], v[80:81], v[158:159], v[192:193]
	v_pk_fma_f32 v[192:193], v[82:83], v[160:161], v[192:193]
	v_pk_fma_f32 v[192:193], v[84:85], v[162:163], v[192:193]
	v_pk_fma_f32 v[192:193], v[86:87], v[164:165], v[192:193]
	v_pk_fma_f32 v[192:193], v[88:89], v[166:167], v[192:193]
	v_pk_fma_f32 v[192:193], v[90:91], v[168:169], v[192:193]
	v_pk_fma_f32 v[192:193], v[92:93], v[170:171], v[192:193]
	v_pk_fma_f32 v[192:193], v[94:95], v[174:175], v[192:193]
	v_fmac_f32_e32 v192, v96, v176
	v_add_f32_e32 v232, v193, v192
	v_fma_f32 v195, v66, v145, v97
	v_mov_b32_e32 v194, 0
	v_pk_fma_f32 v[194:195], v[200:201], v[146:147], v[194:195]
	v_pk_fma_f32 v[194:195], v[202:203], v[148:149], v[194:195]
	v_pk_fma_f32 v[194:195], v[204:205], v[150:151], v[194:195]
	v_pk_fma_f32 v[194:195], v[206:207], v[152:153], v[194:195]
	v_pk_fma_f32 v[194:195], v[208:209], v[154:155], v[194:195]
	v_pk_fma_f32 v[194:195], v[210:211], v[156:157], v[194:195]
	v_pk_fma_f32 v[194:195], v[212:213], v[158:159], v[194:195]
	v_pk_fma_f32 v[194:195], v[214:215], v[160:161], v[194:195]
	v_pk_fma_f32 v[194:195], v[216:217], v[162:163], v[194:195]
	v_pk_fma_f32 v[194:195], v[218:219], v[164:165], v[194:195]
	v_pk_fma_f32 v[194:195], v[220:221], v[166:167], v[194:195]
	v_pk_fma_f32 v[194:195], v[222:223], v[168:169], v[194:195]
	v_pk_fma_f32 v[194:195], v[224:225], v[170:171], v[194:195]
	v_pk_fma_f32 v[194:195], v[226:227], v[174:175], v[194:195]
	v_pk_fma_f32 v[194:195], v[228:229], v[176:177], v[194:195]
	v_add_f32_e32 v233, v194, v195
	ds_write2st64_b32 v100, v232, v233 offset0:128 offset1:136
	v_pk_fma_f32 v[196:197], v[66:67], v[146:147], v[230:231]
	v_pk_fma_f32 v[196:197], v[68:69], v[148:149], v[196:197]
	v_pk_fma_f32 v[196:197], v[70:71], v[150:151], v[196:197]
	v_pk_fma_f32 v[196:197], v[72:73], v[152:153], v[196:197]
	v_pk_fma_f32 v[196:197], v[74:75], v[154:155], v[196:197]
	v_pk_fma_f32 v[196:197], v[76:77], v[156:157], v[196:197]
	v_pk_fma_f32 v[196:197], v[78:79], v[158:159], v[196:197]
	v_pk_fma_f32 v[196:197], v[80:81], v[160:161], v[196:197]
	v_pk_fma_f32 v[196:197], v[82:83], v[162:163], v[196:197]
	v_pk_fma_f32 v[196:197], v[84:85], v[164:165], v[196:197]
	v_pk_fma_f32 v[196:197], v[86:87], v[166:167], v[196:197]
	v_pk_fma_f32 v[196:197], v[88:89], v[168:169], v[196:197]
	v_pk_fma_f32 v[196:197], v[90:91], v[170:171], v[196:197]
	v_pk_fma_f32 v[196:197], v[92:93], v[174:175], v[196:197]
	v_pk_fma_f32 v[196:197], v[94:95], v[176:177], v[196:197]
	v_fmac_f32_e32 v196, v96, v178
	v_add_f32_e32 v234, v197, v196
	v_fma_f32 v199, v66, v147, v97
	v_mov_b32_e32 v198, 0
	v_pk_fma_f32 v[198:199], v[200:201], v[148:149], v[198:199]
	v_pk_fma_f32 v[198:199], v[202:203], v[150:151], v[198:199]
	v_pk_fma_f32 v[198:199], v[204:205], v[152:153], v[198:199]
	v_pk_fma_f32 v[198:199], v[206:207], v[154:155], v[198:199]
	v_pk_fma_f32 v[198:199], v[208:209], v[156:157], v[198:199]
	v_pk_fma_f32 v[198:199], v[210:211], v[158:159], v[198:199]
	v_pk_fma_f32 v[198:199], v[212:213], v[160:161], v[198:199]
	v_pk_fma_f32 v[198:199], v[214:215], v[162:163], v[198:199]
	v_pk_fma_f32 v[198:199], v[216:217], v[164:165], v[198:199]
	v_pk_fma_f32 v[198:199], v[218:219], v[166:167], v[198:199]
	v_pk_fma_f32 v[198:199], v[220:221], v[168:169], v[198:199]
	v_pk_fma_f32 v[198:199], v[222:223], v[170:171], v[198:199]
	v_pk_fma_f32 v[198:199], v[224:225], v[174:175], v[198:199]
	v_pk_fma_f32 v[198:199], v[226:227], v[176:177], v[198:199]
	v_pk_fma_f32 v[198:199], v[228:229], v[178:179], v[198:199]
	v_add_f32_e32 v235, v198, v199
	ds_write2st64_b32 v100, v234, v235 offset0:144 offset1:152
	v_pk_fma_f32 v[192:193], v[66:67], v[148:149], v[230:231]
	v_pk_fma_f32 v[192:193], v[68:69], v[150:151], v[192:193]
	v_pk_fma_f32 v[192:193], v[70:71], v[152:153], v[192:193]
	v_pk_fma_f32 v[192:193], v[72:73], v[154:155], v[192:193]
	v_pk_fma_f32 v[192:193], v[74:75], v[156:157], v[192:193]
	v_pk_fma_f32 v[192:193], v[76:77], v[158:159], v[192:193]
	v_pk_fma_f32 v[192:193], v[78:79], v[160:161], v[192:193]
	v_pk_fma_f32 v[192:193], v[80:81], v[162:163], v[192:193]
	v_pk_fma_f32 v[192:193], v[82:83], v[164:165], v[192:193]
	v_pk_fma_f32 v[192:193], v[84:85], v[166:167], v[192:193]
	v_pk_fma_f32 v[192:193], v[86:87], v[168:169], v[192:193]
	v_pk_fma_f32 v[192:193], v[88:89], v[170:171], v[192:193]
	v_pk_fma_f32 v[192:193], v[90:91], v[174:175], v[192:193]
	v_pk_fma_f32 v[192:193], v[92:93], v[176:177], v[192:193]
	v_pk_fma_f32 v[192:193], v[94:95], v[178:179], v[192:193]
	v_fmac_f32_e32 v192, v96, v180
	v_add_f32_e32 v232, v193, v192
	v_fma_f32 v195, v66, v149, v97
	v_mov_b32_e32 v194, 0
	v_pk_fma_f32 v[194:195], v[200:201], v[150:151], v[194:195]
	v_pk_fma_f32 v[194:195], v[202:203], v[152:153], v[194:195]
	v_pk_fma_f32 v[194:195], v[204:205], v[154:155], v[194:195]
	v_pk_fma_f32 v[194:195], v[206:207], v[156:157], v[194:195]
	v_pk_fma_f32 v[194:195], v[208:209], v[158:159], v[194:195]
	v_pk_fma_f32 v[194:195], v[210:211], v[160:161], v[194:195]
	v_pk_fma_f32 v[194:195], v[212:213], v[162:163], v[194:195]
	v_pk_fma_f32 v[194:195], v[214:215], v[164:165], v[194:195]
	v_pk_fma_f32 v[194:195], v[216:217], v[166:167], v[194:195]
	v_pk_fma_f32 v[194:195], v[218:219], v[168:169], v[194:195]
	v_pk_fma_f32 v[194:195], v[220:221], v[170:171], v[194:195]
	v_pk_fma_f32 v[194:195], v[222:223], v[174:175], v[194:195]
	v_pk_fma_f32 v[194:195], v[224:225], v[176:177], v[194:195]
	v_pk_fma_f32 v[194:195], v[226:227], v[178:179], v[194:195]
	v_pk_fma_f32 v[194:195], v[228:229], v[180:181], v[194:195]
	v_add_f32_e32 v233, v194, v195
	ds_write2st64_b32 v100, v232, v233 offset0:160 offset1:168
	v_pk_fma_f32 v[196:197], v[66:67], v[150:151], v[230:231]
	v_pk_fma_f32 v[196:197], v[68:69], v[152:153], v[196:197]
	v_pk_fma_f32 v[196:197], v[70:71], v[154:155], v[196:197]
	v_pk_fma_f32 v[196:197], v[72:73], v[156:157], v[196:197]
	v_pk_fma_f32 v[196:197], v[74:75], v[158:159], v[196:197]
	v_pk_fma_f32 v[196:197], v[76:77], v[160:161], v[196:197]
	v_pk_fma_f32 v[196:197], v[78:79], v[162:163], v[196:197]
	v_pk_fma_f32 v[196:197], v[80:81], v[164:165], v[196:197]
	v_pk_fma_f32 v[196:197], v[82:83], v[166:167], v[196:197]
	v_pk_fma_f32 v[196:197], v[84:85], v[168:169], v[196:197]
	v_pk_fma_f32 v[196:197], v[86:87], v[170:171], v[196:197]
	v_pk_fma_f32 v[196:197], v[88:89], v[174:175], v[196:197]
	v_pk_fma_f32 v[196:197], v[90:91], v[176:177], v[196:197]
	v_pk_fma_f32 v[196:197], v[92:93], v[178:179], v[196:197]
	v_pk_fma_f32 v[196:197], v[94:95], v[180:181], v[196:197]
	v_fmac_f32_e32 v196, v96, v182
	v_add_f32_e32 v234, v197, v196
	v_fma_f32 v199, v66, v151, v97
	v_mov_b32_e32 v198, 0
	v_pk_fma_f32 v[198:199], v[200:201], v[152:153], v[198:199]
	v_pk_fma_f32 v[198:199], v[202:203], v[154:155], v[198:199]
	v_pk_fma_f32 v[198:199], v[204:205], v[156:157], v[198:199]
	v_pk_fma_f32 v[198:199], v[206:207], v[158:159], v[198:199]
	v_pk_fma_f32 v[198:199], v[208:209], v[160:161], v[198:199]
	v_pk_fma_f32 v[198:199], v[210:211], v[162:163], v[198:199]
	v_pk_fma_f32 v[198:199], v[212:213], v[164:165], v[198:199]
	v_pk_fma_f32 v[198:199], v[214:215], v[166:167], v[198:199]
	v_pk_fma_f32 v[198:199], v[216:217], v[168:169], v[198:199]
	v_pk_fma_f32 v[198:199], v[218:219], v[170:171], v[198:199]
	v_pk_fma_f32 v[198:199], v[220:221], v[174:175], v[198:199]
	v_pk_fma_f32 v[198:199], v[222:223], v[176:177], v[198:199]
	v_pk_fma_f32 v[198:199], v[224:225], v[178:179], v[198:199]
	v_pk_fma_f32 v[198:199], v[226:227], v[180:181], v[198:199]
	v_pk_fma_f32 v[198:199], v[228:229], v[182:183], v[198:199]
	v_add_f32_e32 v235, v198, v199
	ds_write2st64_b32 v100, v234, v235 offset0:176 offset1:184
	v_pk_fma_f32 v[192:193], v[66:67], v[152:153], v[230:231]
	v_pk_fma_f32 v[192:193], v[68:69], v[154:155], v[192:193]
	v_pk_fma_f32 v[192:193], v[70:71], v[156:157], v[192:193]
	v_pk_fma_f32 v[192:193], v[72:73], v[158:159], v[192:193]
	v_pk_fma_f32 v[192:193], v[74:75], v[160:161], v[192:193]
	v_pk_fma_f32 v[192:193], v[76:77], v[162:163], v[192:193]
	v_pk_fma_f32 v[192:193], v[78:79], v[164:165], v[192:193]
	v_pk_fma_f32 v[192:193], v[80:81], v[166:167], v[192:193]
	v_pk_fma_f32 v[192:193], v[82:83], v[168:169], v[192:193]
	v_pk_fma_f32 v[192:193], v[84:85], v[170:171], v[192:193]
	v_pk_fma_f32 v[192:193], v[86:87], v[174:175], v[192:193]
	v_pk_fma_f32 v[192:193], v[88:89], v[176:177], v[192:193]
	v_pk_fma_f32 v[192:193], v[90:91], v[178:179], v[192:193]
	v_pk_fma_f32 v[192:193], v[92:93], v[180:181], v[192:193]
	v_pk_fma_f32 v[192:193], v[94:95], v[182:183], v[192:193]
	v_fmac_f32_e32 v192, v96, v184
	v_add_f32_e32 v232, v193, v192
	v_fma_f32 v195, v66, v153, v97
	v_mov_b32_e32 v194, 0
	v_pk_fma_f32 v[194:195], v[200:201], v[154:155], v[194:195]
	v_pk_fma_f32 v[194:195], v[202:203], v[156:157], v[194:195]
	v_pk_fma_f32 v[194:195], v[204:205], v[158:159], v[194:195]
	v_pk_fma_f32 v[194:195], v[206:207], v[160:161], v[194:195]
	v_pk_fma_f32 v[194:195], v[208:209], v[162:163], v[194:195]
	v_pk_fma_f32 v[194:195], v[210:211], v[164:165], v[194:195]
	v_pk_fma_f32 v[194:195], v[212:213], v[166:167], v[194:195]
	v_pk_fma_f32 v[194:195], v[214:215], v[168:169], v[194:195]
	v_pk_fma_f32 v[194:195], v[216:217], v[170:171], v[194:195]
	v_pk_fma_f32 v[194:195], v[218:219], v[174:175], v[194:195]
	v_pk_fma_f32 v[194:195], v[220:221], v[176:177], v[194:195]
	v_pk_fma_f32 v[194:195], v[222:223], v[178:179], v[194:195]
	v_pk_fma_f32 v[194:195], v[224:225], v[180:181], v[194:195]
	v_pk_fma_f32 v[194:195], v[226:227], v[182:183], v[194:195]
	v_pk_fma_f32 v[194:195], v[228:229], v[184:185], v[194:195]
	v_add_f32_e32 v233, v194, v195
	ds_write2st64_b32 v100, v232, v233 offset0:192 offset1:200
	v_pk_fma_f32 v[196:197], v[66:67], v[154:155], v[230:231]
	v_pk_fma_f32 v[196:197], v[68:69], v[156:157], v[196:197]
	v_pk_fma_f32 v[196:197], v[70:71], v[158:159], v[196:197]
	v_pk_fma_f32 v[196:197], v[72:73], v[160:161], v[196:197]
	v_pk_fma_f32 v[196:197], v[74:75], v[162:163], v[196:197]
	v_pk_fma_f32 v[196:197], v[76:77], v[164:165], v[196:197]
	v_pk_fma_f32 v[196:197], v[78:79], v[166:167], v[196:197]
	v_pk_fma_f32 v[196:197], v[80:81], v[168:169], v[196:197]
	v_pk_fma_f32 v[196:197], v[82:83], v[170:171], v[196:197]
	v_pk_fma_f32 v[196:197], v[84:85], v[174:175], v[196:197]
	v_pk_fma_f32 v[196:197], v[86:87], v[176:177], v[196:197]
	v_pk_fma_f32 v[196:197], v[88:89], v[178:179], v[196:197]
	v_pk_fma_f32 v[196:197], v[90:91], v[180:181], v[196:197]
	v_pk_fma_f32 v[196:197], v[92:93], v[182:183], v[196:197]
	v_pk_fma_f32 v[196:197], v[94:95], v[184:185], v[196:197]
	v_fmac_f32_e32 v196, v96, v186
	v_add_f32_e32 v234, v197, v196
	v_fma_f32 v199, v66, v155, v97
	v_mov_b32_e32 v198, 0
	v_pk_fma_f32 v[198:199], v[200:201], v[156:157], v[198:199]
	v_pk_fma_f32 v[198:199], v[202:203], v[158:159], v[198:199]
	v_pk_fma_f32 v[198:199], v[204:205], v[160:161], v[198:199]
	v_pk_fma_f32 v[198:199], v[206:207], v[162:163], v[198:199]
	v_pk_fma_f32 v[198:199], v[208:209], v[164:165], v[198:199]
	v_pk_fma_f32 v[198:199], v[210:211], v[166:167], v[198:199]
	v_pk_fma_f32 v[198:199], v[212:213], v[168:169], v[198:199]
	v_pk_fma_f32 v[198:199], v[214:215], v[170:171], v[198:199]
	v_pk_fma_f32 v[198:199], v[216:217], v[174:175], v[198:199]
	v_pk_fma_f32 v[198:199], v[218:219], v[176:177], v[198:199]
	v_pk_fma_f32 v[198:199], v[220:221], v[178:179], v[198:199]
	v_pk_fma_f32 v[198:199], v[222:223], v[180:181], v[198:199]
	v_pk_fma_f32 v[198:199], v[224:225], v[182:183], v[198:199]
	v_pk_fma_f32 v[198:199], v[226:227], v[184:185], v[198:199]
	v_pk_fma_f32 v[198:199], v[228:229], v[186:187], v[198:199]
	v_add_f32_e32 v235, v198, v199
	ds_write2st64_b32 v100, v234, v235 offset0:208 offset1:216
	v_pk_fma_f32 v[192:193], v[66:67], v[156:157], v[230:231]
	v_pk_fma_f32 v[192:193], v[68:69], v[158:159], v[192:193]
	v_pk_fma_f32 v[192:193], v[70:71], v[160:161], v[192:193]
	v_pk_fma_f32 v[192:193], v[72:73], v[162:163], v[192:193]
	v_pk_fma_f32 v[192:193], v[74:75], v[164:165], v[192:193]
	v_pk_fma_f32 v[192:193], v[76:77], v[166:167], v[192:193]
	v_pk_fma_f32 v[192:193], v[78:79], v[168:169], v[192:193]
	v_pk_fma_f32 v[192:193], v[80:81], v[170:171], v[192:193]
	v_pk_fma_f32 v[192:193], v[82:83], v[174:175], v[192:193]
	v_pk_fma_f32 v[192:193], v[84:85], v[176:177], v[192:193]
	v_pk_fma_f32 v[192:193], v[86:87], v[178:179], v[192:193]
	v_pk_fma_f32 v[192:193], v[88:89], v[180:181], v[192:193]
	v_pk_fma_f32 v[192:193], v[90:91], v[182:183], v[192:193]
	v_pk_fma_f32 v[192:193], v[92:93], v[184:185], v[192:193]
	v_pk_fma_f32 v[192:193], v[94:95], v[186:187], v[192:193]
	v_fmac_f32_e32 v192, v96, v188
	v_add_f32_e32 v232, v193, v192
	v_fma_f32 v195, v66, v157, v97
	v_mov_b32_e32 v194, 0
	v_pk_fma_f32 v[194:195], v[200:201], v[158:159], v[194:195]
	v_pk_fma_f32 v[194:195], v[202:203], v[160:161], v[194:195]
	v_pk_fma_f32 v[194:195], v[204:205], v[162:163], v[194:195]
	v_pk_fma_f32 v[194:195], v[206:207], v[164:165], v[194:195]
	v_pk_fma_f32 v[194:195], v[208:209], v[166:167], v[194:195]
	v_pk_fma_f32 v[194:195], v[210:211], v[168:169], v[194:195]
	v_pk_fma_f32 v[194:195], v[212:213], v[170:171], v[194:195]
	v_pk_fma_f32 v[194:195], v[214:215], v[174:175], v[194:195]
	v_pk_fma_f32 v[194:195], v[216:217], v[176:177], v[194:195]
	v_pk_fma_f32 v[194:195], v[218:219], v[178:179], v[194:195]
	v_pk_fma_f32 v[194:195], v[220:221], v[180:181], v[194:195]
	v_pk_fma_f32 v[194:195], v[222:223], v[182:183], v[194:195]
	v_pk_fma_f32 v[194:195], v[224:225], v[184:185], v[194:195]
	v_pk_fma_f32 v[194:195], v[226:227], v[186:187], v[194:195]
	v_pk_fma_f32 v[194:195], v[228:229], v[188:189], v[194:195]
	v_add_f32_e32 v233, v194, v195
	ds_write2st64_b32 v100, v232, v233 offset0:224 offset1:232
	v_pk_fma_f32 v[196:197], v[66:67], v[158:159], v[230:231]
	v_pk_fma_f32 v[196:197], v[68:69], v[160:161], v[196:197]
	v_pk_fma_f32 v[196:197], v[70:71], v[162:163], v[196:197]
	v_pk_fma_f32 v[196:197], v[72:73], v[164:165], v[196:197]
	v_pk_fma_f32 v[196:197], v[74:75], v[166:167], v[196:197]
	v_pk_fma_f32 v[196:197], v[76:77], v[168:169], v[196:197]
	v_pk_fma_f32 v[196:197], v[78:79], v[170:171], v[196:197]
	v_pk_fma_f32 v[196:197], v[80:81], v[174:175], v[196:197]
	v_pk_fma_f32 v[196:197], v[82:83], v[176:177], v[196:197]
	v_pk_fma_f32 v[196:197], v[84:85], v[178:179], v[196:197]
	v_pk_fma_f32 v[196:197], v[86:87], v[180:181], v[196:197]
	v_pk_fma_f32 v[196:197], v[88:89], v[182:183], v[196:197]
	v_pk_fma_f32 v[196:197], v[90:91], v[184:185], v[196:197]
	v_pk_fma_f32 v[196:197], v[92:93], v[186:187], v[196:197]
	v_pk_fma_f32 v[196:197], v[94:95], v[188:189], v[196:197]
	v_fmac_f32_e32 v196, v96, v190
	v_add_f32_e32 v234, v197, v196
	v_fma_f32 v199, v66, v159, v97
	v_mov_b32_e32 v198, 0
	v_pk_fma_f32 v[198:199], v[200:201], v[160:161], v[198:199]
	v_pk_fma_f32 v[198:199], v[202:203], v[162:163], v[198:199]
	v_pk_fma_f32 v[198:199], v[204:205], v[164:165], v[198:199]
	v_pk_fma_f32 v[198:199], v[206:207], v[166:167], v[198:199]
	v_pk_fma_f32 v[198:199], v[208:209], v[168:169], v[198:199]
	v_pk_fma_f32 v[198:199], v[210:211], v[170:171], v[198:199]
	v_pk_fma_f32 v[198:199], v[212:213], v[174:175], v[198:199]
	v_pk_fma_f32 v[198:199], v[214:215], v[176:177], v[198:199]
	v_pk_fma_f32 v[198:199], v[216:217], v[178:179], v[198:199]
	v_pk_fma_f32 v[198:199], v[218:219], v[180:181], v[198:199]
	v_pk_fma_f32 v[198:199], v[220:221], v[182:183], v[198:199]
	v_pk_fma_f32 v[198:199], v[222:223], v[184:185], v[198:199]
	v_pk_fma_f32 v[198:199], v[224:225], v[186:187], v[198:199]
	v_pk_fma_f32 v[198:199], v[226:227], v[188:189], v[198:199]
	v_pk_fma_f32 v[198:199], v[228:229], v[190:191], v[198:199]
	v_add_f32_e32 v235, v198, v199
	ds_write2st64_b32 v100, v234, v235 offset0:240 offset1:248
	s_waitcnt lgkmcnt(0)
	s_barrier
	ds_read_b128 v[128:131], v122
	ds_read_b128 v[132:135], v122 offset:16
	s_ashr_i32 s0, s40, 31
	s_lshr_b32 s0, s0, 26
	s_add_i32 s1, s40, s0
	s_waitcnt lgkmcnt(1)
	v_mov_b32_e32 v34, v129
	v_mov_b32_e32 v35, v130
	v_mov_b32_e32 v64, v128
	v_mov_b32_e32 v65, v131
	v_pk_add_f32 v[34:35], v[34:35], v[64:65]
	s_waitcnt lgkmcnt(0)
	v_mov_b32_e32 v64, v134
	v_mov_b32_e32 v65, v132
	v_mov_b32_e32 v136, v135
	v_mov_b32_e32 v137, v133
	v_pk_add_f32 v[64:65], v[64:65], v[136:137]
	v_add_f32_e32 v33, v34, v35
	v_add_f32_e32 v33, v33, v65
	v_add_f32_e32 v33, v64, v33
	ds_bpermute_b32 v34, v101, v33
	s_ashr_i32 s0, s1, 6
	s_and_b32 s1, s1, 0x7ffffc0
	s_sub_i32 s20, s40, s1
	s_ashr_i32 s1, s0, 31
	s_waitcnt lgkmcnt(0)
	v_add_f32_e32 v33, v33, v34
	ds_bpermute_b32 v34, v102, v33
	s_lshl_b32 s33, s20, 5
	s_lshl_b64 s[20:21], s[0:1], 11
	s_waitcnt lgkmcnt(0)
	v_add_f32_e32 v33, v33, v34
	ds_bpermute_b32 v34, v103, v33
	s_waitcnt lgkmcnt(0)
	v_add_f32_e32 v33, v33, v34
	ds_bpermute_b32 v34, v104, v33
	s_waitcnt lgkmcnt(0)
	v_add_f32_e32 v33, v33, v34
	ds_bpermute_b32 v34, v105, v33
	s_waitcnt lgkmcnt(0)
	v_add_f32_e32 v33, v33, v34
	ds_bpermute_b32 v34, v106, v33
	s_waitcnt lgkmcnt(0)
	v_add_f32_e32 v33, v33, v34
	v_fmamk_f32 v35, v33, 0xbb000000, v131
	v_fmac_f32_e32 v129, 0xbb000000, v33
	v_fmamk_f32 v34, v33, 0xbb000000, v130
	v_fmamk_f32 v128, v33, 0xbb000000, v128
	v_fmamk_f32 v65, v33, 0xbb000000, v133
	v_fmamk_f32 v64, v33, 0xbb000000, v132
	v_fmamk_f32 v135, v33, 0xbb000000, v135
	v_fmac_f32_e32 v134, 0xbb000000, v33
	v_mul_f32_e32 v33, v129, v129
	v_mul_f32_e32 v130, v35, v35
	v_fmac_f32_e32 v33, v128, v128
	v_fmac_f32_e32 v130, v34, v34
	v_add_f32_e32 v33, v33, v130
	v_pk_mul_f32 v[130:131], v[134:135], v[134:135]
	v_pk_mul_f32 v[132:133], v[64:65], v[64:65]
	v_mov_b32_e32 v136, v130
	v_mov_b32_e32 v137, v132
	v_mov_b32_e32 v132, v131
	v_pk_add_f32 v[130:131], v[136:137], v[132:133]
	s_nop 0
	v_add_f32_e32 v33, v131, v33
	v_add_f32_e32 v33, v130, v33
	ds_bpermute_b32 v130, v101, v33
	s_waitcnt lgkmcnt(0)
	v_add_f32_e32 v33, v33, v130
	ds_bpermute_b32 v130, v102, v33
	s_waitcnt lgkmcnt(0)
	v_add_f32_e32 v33, v33, v130
	ds_bpermute_b32 v130, v103, v33
	s_waitcnt lgkmcnt(0)
	v_add_f32_e32 v33, v33, v130
	ds_bpermute_b32 v130, v104, v33
	s_waitcnt lgkmcnt(0)
	v_add_f32_e32 v33, v33, v130
	ds_bpermute_b32 v130, v105, v33
	s_waitcnt lgkmcnt(0)
	v_add_f32_e32 v33, v33, v130
	ds_bpermute_b32 v130, v106, v33
	s_waitcnt lgkmcnt(0)
	v_add_f32_e32 v33, v33, v130
	v_fmamk_f32 v33, v33, 0x3b000000, v123
	v_mul_f32_e32 v130, 0x4f800000, v33
	v_cmp_gt_f32_e32 vcc, s45, v33
	s_nop 1
	v_cndmask_b32_e32 v33, v33, v130, vcc
	v_sqrt_f32_e32 v130, v33
	s_nop 0
	v_add_u32_e32 v131, -1, v130
	v_fma_f32 v132, -v131, v130, v33
	v_cmp_ge_f32_e64 s[0:1], 0, v132
	v_add_u32_e32 v132, 1, v130
	s_nop 0
	v_cndmask_b32_e64 v131, v130, v131, s[0:1]
	v_fma_f32 v130, -v132, v130, v33
	v_cmp_lt_f32_e64 s[0:1], 0, v130
	s_nop 1
	v_cndmask_b32_e64 v130, v131, v132, s[0:1]
	v_mul_f32_e32 v131, 0x37800000, v130
	v_cndmask_b32_e32 v130, v130, v131, vcc
	v_cmp_class_f32_e32 vcc, v33, v124
	s_nop 1
	v_cndmask_b32_e32 v33, v130, v33, vcc
	v_div_scale_f32 v130, s[0:1], v33, v33, 1.0
	v_rcp_f32_e32 v131, v130
	s_ashr_i32 s0, s33, 31
	s_add_u32 s40, s20, s33
	s_addc_u32 s41, s21, s0
	v_fma_f32 v132, -v130, v131, 1.0
	v_fmac_f32_e32 v131, v132, v131
	v_div_scale_f32 v132, vcc, 1.0, v33, 1.0
	v_mul_f32_e32 v133, v132, v131
	v_fma_f32 v136, -v130, v133, v132
	v_fmac_f32_e32 v133, v136, v131
	v_fma_f32 v130, -v130, v133, v132
	v_div_fmas_f32 v130, v130, v131, v133
	v_div_fixup_f32 v130, v130, v33, 1.0
	v_pk_mul_f32 v[128:129], v[128:129], v[130:131] op_sel_hi:[1,0]
	v_pk_mul_f32 v[64:65], v[64:65], v[130:131] op_sel_hi:[1,0]
	s_waitcnt vmcnt(0)
	v_pk_fma_f32 v[136:137], v[8:9], v[128:129], v[12:13]
	v_pk_mul_f32 v[128:129], v[134:135], v[130:131] op_sel_hi:[1,0]
	v_pk_fma_f32 v[64:65], v[0:1], v[64:65], v[4:5]
	v_mul_f32_e32 v33, 0xbfb8aa3b, v136
	v_pk_mul_f32 v[34:35], v[34:35], v[130:131] op_sel_hi:[1,0]
	v_exp_f32_e32 v33, v33
	v_mul_f32_e32 v130, 0xbfb8aa3b, v64
	v_pk_fma_f32 v[138:139], v[2:3], v[128:129], v[6:7]
	v_mul_f32_e32 v128, 0xbfb8aa3b, v137
	v_exp_f32_e32 v130, v130
	v_exp_f32_e32 v128, v128
	v_add_f32_e32 v33, 1.0, v33
	v_rcp_f32_e32 v140, v33
	v_add_f32_e32 v33, 1.0, v130
	v_add_f32_e32 v132, 1.0, v128
	ds_read_b128 v[128:131], v125
	v_rcp_f32_e32 v142, v33
	v_mul_f32_e32 v33, 0xbfb8aa3b, v65
	v_rcp_f32_e32 v144, v132
	ds_read_b128 v[132:135], v125 offset:16
	v_exp_f32_e32 v33, v33
	s_waitcnt lgkmcnt(1)
	v_mov_b32_e32 v148, v129
	v_mov_b32_e32 v149, v130
	v_mov_b32_e32 v150, v128
	v_mov_b32_e32 v151, v131
	v_add_f32_e32 v33, 1.0, v33
	v_pk_add_f32 v[148:149], v[148:149], v[150:151]
	s_waitcnt lgkmcnt(0)
	v_mov_b32_e32 v150, v134
	v_mov_b32_e32 v151, v132
	v_mov_b32_e32 v152, v135
	v_mov_b32_e32 v153, v133
	v_rcp_f32_e32 v146, v33
	v_pk_add_f32 v[150:151], v[150:151], v[152:153]
	v_add_f32_e32 v33, v148, v149
	v_add_f32_e32 v33, v33, v151
	v_add_f32_e32 v33, v150, v33
	ds_bpermute_b32 v141, v101, v33
	v_pk_fma_f32 v[34:35], v[10:11], v[34:35], v[14:15]
	v_mul_f32_e32 v145, 0xbfb8aa3b, v138
	v_mul_f32_e32 v143, 0xbfb8aa3b, v34
	v_exp_f32_e32 v143, v143
	s_waitcnt lgkmcnt(0)
	v_add_f32_e32 v33, v33, v141
	ds_bpermute_b32 v147, v102, v33
	v_exp_f32_e32 v145, v145
	v_add_f32_e32 v141, 1.0, v143
	v_mul_f32_e32 v148, 0xbfb8aa3b, v139
	v_exp_f32_e32 v148, v148
	s_waitcnt lgkmcnt(0)
	v_add_f32_e32 v33, v33, v147
	v_add_f32_e32 v143, 1.0, v145
	ds_bpermute_b32 v145, v103, v33
	v_mul_f32_e32 v147, 0xbfb8aa3b, v35
	v_exp_f32_e32 v147, v147
	v_rcp_f32_e32 v141, v141
	v_rcp_f32_e32 v143, v143
	s_waitcnt lgkmcnt(0)
	v_add_f32_e32 v33, v33, v145
	ds_bpermute_b32 v149, v104, v33
	v_add_f32_e32 v145, 1.0, v147
	v_add_f32_e32 v147, 1.0, v148
	v_mov_b32_e32 v148, v136
	v_rcp_f32_e32 v145, v145
	s_waitcnt lgkmcnt(0)
	v_add_f32_e32 v33, v33, v149
	ds_bpermute_b32 v150, v105, v33
	v_mov_b32_e32 v149, v34
	v_pk_mul_f32 v[140:141], v[148:149], v[140:141]
	v_mov_b32_e32 v34, v137
	v_mov_b32_e32 v136, v64
	s_waitcnt lgkmcnt(0)
	v_add_f32_e32 v33, v33, v150
	ds_bpermute_b32 v148, v106, v33
	v_mov_b32_e32 v137, v138
	v_pk_mul_f32 v[34:35], v[34:35], v[144:145]
	v_pk_mul_f32 v[136:137], v[136:137], v[142:143]
	v_rcp_f32_e32 v147, v147
	s_waitcnt lgkmcnt(0)
	v_add_f32_e32 v33, v33, v148
	v_fmamk_f32 v143, v33, 0xbb000000, v131
	v_fmac_f32_e32 v129, 0xbb000000, v33
	v_fmamk_f32 v145, v33, 0xbb000000, v133
	v_fmamk_f32 v144, v33, 0xbb000000, v132
	v_fmamk_f32 v135, v33, 0xbb000000, v135
	v_fmac_f32_e32 v134, 0xbb000000, v33
	v_fmamk_f32 v142, v33, 0xbb000000, v130
	v_fmamk_f32 v128, v33, 0xbb000000, v128
	v_mul_f32_e32 v33, v129, v129
	v_mul_f32_e32 v64, v143, v143
	v_pk_mul_f32 v[130:131], v[134:135], v[134:135]
	v_pk_mul_f32 v[132:133], v[144:145], v[144:145]
	v_fmac_f32_e32 v33, v128, v128
	v_fmac_f32_e32 v64, v142, v142
	v_mov_b32_e32 v148, v130
	v_mov_b32_e32 v149, v132
	v_mov_b32_e32 v132, v131
	v_add_f32_e32 v33, v33, v64
	v_pk_add_f32 v[130:131], v[148:149], v[132:133]
	v_mov_b32_e32 v138, v65
	v_add_f32_e32 v33, v131, v33
	v_add_f32_e32 v33, v130, v33
	ds_bpermute_b32 v130, v101, v33
	v_pk_mul_f32 v[64:65], v[138:139], v[146:147]
	v_bfe_u32 v133, v35, 16, 1
	v_bfe_u32 v131, v65, 16, 1
	v_bfe_u32 v132, v64, 16, 1
	s_waitcnt lgkmcnt(0)
	v_add_f32_e32 v33, v33, v130
	ds_bpermute_b32 v130, v102, v33
	v_add3_u32 v35, v35, v133, s52
	v_add3_u32 v64, v64, v132, s52
	v_add3_u32 v65, v65, v131, s52
	v_bfe_u32 v131, v140, 16, 1
	s_waitcnt lgkmcnt(0)
	v_add_f32_e32 v33, v33, v130
	ds_bpermute_b32 v130, v103, v33
	v_bfe_u32 v132, v141, 16, 1
	v_bfe_u32 v133, v136, 16, 1
	v_add3_u32 v133, v136, v133, s52
	v_add3_u32 v132, v141, v132, s52
	s_waitcnt lgkmcnt(0)
	v_add_f32_e32 v33, v33, v130
	ds_bpermute_b32 v130, v104, v33
	v_add3_u32 v131, v140, v131, s52
	v_lshrrev_b32_e32 v136, 16, v131
	v_lshrrev_b32_e32 v131, 16, v132
	v_lshrrev_b32_e32 v132, 16, v133
	s_waitcnt lgkmcnt(0)
	v_add_f32_e32 v33, v33, v130
	ds_bpermute_b32 v130, v105, v33
	v_and_or_b32 v132, v64, s53, v132
	v_bfe_u32 v138, v34, 16, 1
	v_add3_u32 v34, v34, v138, s52
	v_bfe_u32 v138, v137, 16, 1
	s_waitcnt lgkmcnt(0)
	v_add_f32_e32 v33, v33, v130
	ds_bpermute_b32 v130, v106, v33
	v_add3_u32 v137, v137, v138, s52
	v_lshrrev_b32_e32 v133, 16, v137
	v_and_or_b32 v133, v65, s53, v133
	v_and_or_b32 v131, v35, s53, v131
	s_waitcnt lgkmcnt(0)
	v_add_f32_e32 v33, v33, v130
	v_fmamk_f32 v33, v33, 0x3b000000, v123
	v_mul_f32_e32 v64, 0x4f800000, v33
	v_cmp_gt_f32_e32 vcc, s45, v33
	v_and_or_b32 v130, v34, s53, v136
	v_lshl_add_u64 v[34:35], s[40:41], 0, v[54:55]
	v_cndmask_b32_e32 v33, v33, v64, vcc
	v_sqrt_f32_e32 v64, v33
	v_lshlrev_b64 v[34:35], 11, v[34:35]
	v_lshl_add_u64 v[34:35], v[62:63], 0, v[34:35]
	global_store_dwordx4 v[34:35], v[130:133], off offset:1024
	v_add_u32_e32 v65, -1, v64
	v_fma_f32 v136, -v65, v64, v33
	v_cmp_ge_f32_e64 s[0:1], 0, v136
	v_add_u32_e32 v136, 1, v64
	s_add_i32 s43, s43, 32
	v_cndmask_b32_e64 v65, v64, v65, s[0:1]
	v_fma_f32 v64, -v136, v64, v33
	v_cmp_lt_f32_e64 s[0:1], 0, v64
	s_cmp_lg_u32 s42, s44
	s_nop 0
	v_cndmask_b32_e64 v64, v65, v136, s[0:1]
	v_mul_f32_e32 v65, 0x37800000, v64
	v_cndmask_b32_e32 v64, v64, v65, vcc
	v_cmp_class_f32_e32 vcc, v33, v124
	s_nop 1
	v_cndmask_b32_e32 v33, v64, v33, vcc
	v_div_scale_f32 v64, s[0:1], v33, v33, 1.0
	v_rcp_f32_e32 v65, v64
	s_nop 0
	v_fma_f32 v34, -v64, v65, 1.0
	v_fmac_f32_e32 v65, v34, v65
	v_div_scale_f32 v34, vcc, 1.0, v33, 1.0
	v_mul_f32_e32 v35, v34, v65
	v_fma_f32 v130, -v64, v35, v34
	v_fmac_f32_e32 v35, v130, v65
	v_fma_f32 v34, -v64, v35, v34
	v_div_fmas_f32 v34, v34, v65, v35
	v_div_fixup_f32 v34, v34, v33, 1.0
	v_pk_mul_f32 v[64:65], v[128:129], v[34:35] op_sel_hi:[1,0]
	v_pk_mul_f32 v[128:129], v[142:143], v[34:35] op_sel_hi:[1,0]
	v_pk_fma_f32 v[64:65], v[8:9], v[64:65], v[12:13]
	v_pk_fma_f32 v[136:137], v[10:11], v[128:129], v[14:15]
	v_pk_mul_f32 v[128:129], v[144:145], v[34:35] op_sel_hi:[1,0]
	v_mul_f32_e32 v33, 0xbfb8aa3b, v64
	v_pk_fma_f32 v[138:139], v[0:1], v[128:129], v[4:5]
	v_exp_f32_e32 v33, v33
	v_mul_f32_e32 v128, 0xbfb8aa3b, v138
	v_exp_f32_e32 v128, v128
	v_pk_mul_f32 v[34:35], v[134:135], v[34:35] op_sel_hi:[1,0]
	v_add_f32_e32 v33, 1.0, v33
	v_rcp_f32_e32 v140, v33
	v_add_f32_e32 v33, 1.0, v128
	v_mul_f32_e32 v128, 0xbfb8aa3b, v65
	v_exp_f32_e32 v128, v128
	v_rcp_f32_e32 v142, v33
	v_mul_f32_e32 v33, 0xbfb8aa3b, v139
	v_exp_f32_e32 v33, v33
	v_add_f32_e32 v132, 1.0, v128
	ds_read_b128 v[128:131], v126
	v_rcp_f32_e32 v144, v132
	ds_read_b128 v[132:135], v126 offset:16
	v_add_f32_e32 v33, 1.0, v33
	v_rcp_f32_e32 v146, v33
	s_waitcnt lgkmcnt(1)
	v_mov_b32_e32 v148, v129
	v_mov_b32_e32 v149, v130
	v_mov_b32_e32 v150, v128
	v_mov_b32_e32 v151, v131
	v_pk_add_f32 v[148:149], v[148:149], v[150:151]
	s_waitcnt lgkmcnt(0)
	v_mov_b32_e32 v150, v134
	v_mov_b32_e32 v151, v132
	v_mov_b32_e32 v152, v135
	v_mov_b32_e32 v153, v133
	v_pk_add_f32 v[150:151], v[150:151], v[152:153]
	v_add_f32_e32 v33, v148, v149
	v_add_f32_e32 v33, v33, v151
	v_add_f32_e32 v33, v150, v33
	ds_bpermute_b32 v141, v101, v33
	v_pk_fma_f32 v[34:35], v[2:3], v[34:35], v[6:7]
	v_mul_f32_e32 v143, 0xbfb8aa3b, v136
	v_mul_f32_e32 v145, 0xbfb8aa3b, v34
	v_exp_f32_e32 v143, v143
	s_waitcnt lgkmcnt(0)
	v_add_f32_e32 v33, v33, v141
	ds_bpermute_b32 v147, v102, v33
	v_exp_f32_e32 v145, v145
	v_add_f32_e32 v141, 1.0, v143
	v_mul_f32_e32 v148, 0xbfb8aa3b, v35
	v_exp_f32_e32 v148, v148
	s_waitcnt lgkmcnt(0)
	v_add_f32_e32 v33, v33, v147
	v_add_f32_e32 v143, 1.0, v145
	ds_bpermute_b32 v145, v103, v33
	v_mul_f32_e32 v147, 0xbfb8aa3b, v137
	v_exp_f32_e32 v147, v147
	v_rcp_f32_e32 v141, v141
	v_rcp_f32_e32 v143, v143
	s_waitcnt lgkmcnt(0)
	v_add_f32_e32 v33, v33, v145
	ds_bpermute_b32 v149, v104, v33
	v_add_f32_e32 v145, 1.0, v147
	v_add_f32_e32 v147, 1.0, v148
	v_mov_b32_e32 v148, v64
	v_rcp_f32_e32 v145, v145
	s_waitcnt lgkmcnt(0)
	v_add_f32_e32 v33, v33, v149
	ds_bpermute_b32 v150, v105, v33
	v_mov_b32_e32 v149, v136
	v_pk_mul_f32 v[140:141], v[148:149], v[140:141]
	v_mov_b32_e32 v136, v65
	v_pk_mul_f32 v[64:65], v[136:137], v[144:145]
	s_waitcnt lgkmcnt(0)
	v_add_f32_e32 v33, v33, v150
	ds_bpermute_b32 v148, v106, v33
	v_mov_b32_e32 v136, v138
	v_mov_b32_e32 v137, v34
	v_pk_mul_f32 v[136:137], v[136:137], v[142:143]
	v_rcp_f32_e32 v147, v147
	s_waitcnt lgkmcnt(0)
	v_add_f32_e32 v33, v33, v148
	v_fmamk_f32 v143, v33, 0xbb000000, v131
	v_fmac_f32_e32 v129, 0xbb000000, v33
	v_fmamk_f32 v145, v33, 0xbb000000, v133
	v_fmamk_f32 v144, v33, 0xbb000000, v132
	v_fmamk_f32 v135, v33, 0xbb000000, v135
	v_fmac_f32_e32 v134, 0xbb000000, v33
	v_fmamk_f32 v142, v33, 0xbb000000, v130
	v_fmamk_f32 v128, v33, 0xbb000000, v128
	v_mul_f32_e32 v33, v129, v129
	v_mul_f32_e32 v34, v143, v143
	v_pk_mul_f32 v[130:131], v[134:135], v[134:135]
	v_pk_mul_f32 v[132:133], v[144:145], v[144:145]
	v_fmac_f32_e32 v33, v128, v128
	v_fmac_f32_e32 v34, v142, v142
	v_mov_b32_e32 v148, v130
	v_mov_b32_e32 v149, v132
	v_mov_b32_e32 v132, v131
	v_add_f32_e32 v33, v33, v34
	v_pk_add_f32 v[130:131], v[148:149], v[132:133]
	v_mov_b32_e32 v34, v139
	v_add_f32_e32 v33, v131, v33
	v_add_f32_e32 v33, v130, v33
	ds_bpermute_b32 v130, v101, v33
	v_pk_mul_f32 v[34:35], v[34:35], v[146:147]
	v_bfe_u32 v133, v65, 16, 1
	v_bfe_u32 v131, v35, 16, 1
	v_bfe_u32 v132, v34, 16, 1
	s_waitcnt lgkmcnt(0)
	v_add_f32_e32 v33, v33, v130
	ds_bpermute_b32 v130, v102, v33
	v_add3_u32 v65, v65, v133, s52
	v_add3_u32 v34, v34, v132, s52
	v_add3_u32 v35, v35, v131, s52
	v_bfe_u32 v131, v140, 16, 1
	s_waitcnt lgkmcnt(0)
	v_add_f32_e32 v33, v33, v130
	ds_bpermute_b32 v130, v103, v33
	v_bfe_u32 v132, v141, 16, 1
	v_bfe_u32 v133, v136, 16, 1
	v_add3_u32 v133, v136, v133, s52
	v_add3_u32 v132, v141, v132, s52
	s_waitcnt lgkmcnt(0)
	v_add_f32_e32 v33, v33, v130
	ds_bpermute_b32 v130, v104, v33
	v_add3_u32 v131, v140, v131, s52
	v_bfe_u32 v138, v64, 16, 1
	v_lshrrev_b32_e32 v136, 16, v131
	v_lshrrev_b32_e32 v131, 16, v132
	s_waitcnt lgkmcnt(0)
	v_add_f32_e32 v33, v33, v130
	ds_bpermute_b32 v130, v105, v33
	v_lshrrev_b32_e32 v132, 16, v133
	v_add3_u32 v64, v64, v138, s52
	v_bfe_u32 v138, v137, 16, 1
	v_and_or_b32 v132, v34, s53, v132
	s_waitcnt lgkmcnt(0)
	v_add_f32_e32 v33, v33, v130
	ds_bpermute_b32 v130, v106, v33
	v_add3_u32 v137, v137, v138, s52
	v_lshrrev_b32_e32 v133, 16, v137
	v_and_or_b32 v131, v65, s53, v131
	v_and_or_b32 v133, v35, s53, v133
	s_waitcnt lgkmcnt(0)
	v_add_f32_e32 v33, v33, v130
	v_fmamk_f32 v33, v33, 0x3b000000, v123
	v_mul_f32_e32 v34, 0x4f800000, v33
	v_cmp_gt_f32_e32 vcc, s45, v33
	v_and_or_b32 v130, v64, s53, v136
	s_nop 0
	v_cndmask_b32_e32 v33, v33, v34, vcc
	v_sqrt_f32_e32 v137, v33
	v_lshl_add_u64 v[34:35], s[40:41], 0, v[56:57]
	v_lshlrev_b64 v[34:35], 11, v[34:35]
	v_lshl_add_u64 v[34:35], v[62:63], 0, v[34:35]
	v_add_u32_e32 v64, -1, v137
	v_fma_f32 v65, -v64, v137, v33
	v_cmp_ge_f32_e64 s[0:1], 0, v65
	v_add_u32_e32 v65, 1, v137
	v_fma_f32 v136, -v65, v137, v33
	v_cndmask_b32_e64 v64, v137, v64, s[0:1]
	v_cmp_lt_f32_e64 s[0:1], 0, v136
	global_store_dwordx4 v[34:35], v[130:133], off offset:1024
	s_nop 0
	v_cndmask_b32_e64 v64, v64, v65, s[0:1]
	v_mul_f32_e32 v65, 0x37800000, v64
	v_cndmask_b32_e32 v64, v64, v65, vcc
	v_cmp_class_f32_e32 vcc, v33, v124
	s_nop 1
	v_cndmask_b32_e32 v33, v64, v33, vcc
	v_div_scale_f32 v64, s[0:1], v33, v33, 1.0
	v_rcp_f32_e32 v65, v64
	s_nop 0
	v_fma_f32 v34, -v64, v65, 1.0
	v_fmac_f32_e32 v65, v34, v65
	v_div_scale_f32 v34, vcc, 1.0, v33, 1.0
	v_mul_f32_e32 v35, v34, v65
	v_fma_f32 v130, -v64, v35, v34
	v_fmac_f32_e32 v35, v130, v65
	v_fma_f32 v34, -v64, v35, v34
	v_div_fmas_f32 v34, v34, v65, v35
	v_div_fixup_f32 v34, v34, v33, 1.0
	v_pk_mul_f32 v[64:65], v[128:129], v[34:35] op_sel_hi:[1,0]
	v_pk_mul_f32 v[128:129], v[142:143], v[34:35] op_sel_hi:[1,0]
	v_pk_fma_f32 v[64:65], v[8:9], v[64:65], v[12:13]
	v_pk_fma_f32 v[136:137], v[10:11], v[128:129], v[14:15]
	v_pk_mul_f32 v[128:129], v[144:145], v[34:35] op_sel_hi:[1,0]
	v_mul_f32_e32 v33, 0xbfb8aa3b, v64
	v_pk_fma_f32 v[138:139], v[0:1], v[128:129], v[4:5]
	v_exp_f32_e32 v33, v33
	v_mul_f32_e32 v128, 0xbfb8aa3b, v138
	v_exp_f32_e32 v128, v128
	v_pk_mul_f32 v[34:35], v[134:135], v[34:35] op_sel_hi:[1,0]
	v_add_f32_e32 v33, 1.0, v33
	v_rcp_f32_e32 v140, v33
	v_add_f32_e32 v33, 1.0, v128
	v_mul_f32_e32 v128, 0xbfb8aa3b, v65
	v_exp_f32_e32 v128, v128
	v_rcp_f32_e32 v142, v33
	v_mul_f32_e32 v33, 0xbfb8aa3b, v139
	v_exp_f32_e32 v33, v33
	v_add_f32_e32 v132, 1.0, v128
	ds_read_b128 v[128:131], v127
	v_rcp_f32_e32 v144, v132
	ds_read_b128 v[132:135], v127 offset:16
	v_add_f32_e32 v33, 1.0, v33
	v_rcp_f32_e32 v146, v33
	s_waitcnt lgkmcnt(1)
	v_mov_b32_e32 v148, v129
	v_mov_b32_e32 v149, v130
	v_mov_b32_e32 v150, v128
	v_mov_b32_e32 v151, v131
	v_pk_add_f32 v[148:149], v[148:149], v[150:151]
	s_waitcnt lgkmcnt(0)
	v_mov_b32_e32 v150, v134
	v_mov_b32_e32 v151, v132
	v_mov_b32_e32 v152, v135
	v_mov_b32_e32 v153, v133
	v_pk_add_f32 v[150:151], v[150:151], v[152:153]
	v_add_f32_e32 v33, v148, v149
	v_add_f32_e32 v33, v33, v151
	v_add_f32_e32 v33, v150, v33
	ds_bpermute_b32 v141, v101, v33
	v_pk_fma_f32 v[34:35], v[2:3], v[34:35], v[6:7]
	v_mul_f32_e32 v143, 0xbfb8aa3b, v136
	v_mul_f32_e32 v145, 0xbfb8aa3b, v34
	v_exp_f32_e32 v143, v143
	s_waitcnt lgkmcnt(0)
	v_add_f32_e32 v33, v33, v141
	ds_bpermute_b32 v147, v102, v33
	v_exp_f32_e32 v145, v145
	v_add_f32_e32 v141, 1.0, v143
	v_mul_f32_e32 v148, 0xbfb8aa3b, v35
	v_exp_f32_e32 v148, v148
	s_waitcnt lgkmcnt(0)
	v_add_f32_e32 v33, v33, v147
	v_add_f32_e32 v143, 1.0, v145
	ds_bpermute_b32 v145, v103, v33
	v_mul_f32_e32 v147, 0xbfb8aa3b, v137
	v_exp_f32_e32 v147, v147
	v_rcp_f32_e32 v141, v141
	v_rcp_f32_e32 v143, v143
	s_waitcnt lgkmcnt(0)
	v_add_f32_e32 v33, v33, v145
	ds_bpermute_b32 v149, v104, v33
	v_add_f32_e32 v145, 1.0, v147
	v_add_f32_e32 v147, 1.0, v148
	v_mov_b32_e32 v148, v64
	v_rcp_f32_e32 v145, v145
	s_waitcnt lgkmcnt(0)
	v_add_f32_e32 v33, v33, v149
	ds_bpermute_b32 v150, v105, v33
	v_mov_b32_e32 v149, v136
	v_pk_mul_f32 v[140:141], v[148:149], v[140:141]
	v_mov_b32_e32 v136, v65
	v_pk_mul_f32 v[64:65], v[136:137], v[144:145]
	s_waitcnt lgkmcnt(0)
	v_add_f32_e32 v33, v33, v150
	ds_bpermute_b32 v148, v106, v33
	v_mov_b32_e32 v136, v138
	v_mov_b32_e32 v137, v34
	v_pk_mul_f32 v[136:137], v[136:137], v[142:143]
	v_rcp_f32_e32 v147, v147
	s_waitcnt lgkmcnt(0)
	v_add_f32_e32 v33, v33, v148
	v_fmamk_f32 v143, v33, 0xbb000000, v131
	v_fmac_f32_e32 v129, 0xbb000000, v33
	v_fmamk_f32 v145, v33, 0xbb000000, v133
	v_fmamk_f32 v144, v33, 0xbb000000, v132
	v_fmamk_f32 v135, v33, 0xbb000000, v135
	v_fmac_f32_e32 v134, 0xbb000000, v33
	v_fmamk_f32 v142, v33, 0xbb000000, v130
	v_fmamk_f32 v128, v33, 0xbb000000, v128
	v_mul_f32_e32 v33, v129, v129
	v_mul_f32_e32 v34, v143, v143
	v_pk_mul_f32 v[130:131], v[134:135], v[134:135]
	v_pk_mul_f32 v[132:133], v[144:145], v[144:145]
	v_fmac_f32_e32 v33, v128, v128
	v_fmac_f32_e32 v34, v142, v142
	v_mov_b32_e32 v148, v130
	v_mov_b32_e32 v149, v132
	v_mov_b32_e32 v132, v131
	v_add_f32_e32 v33, v33, v34
	v_pk_add_f32 v[130:131], v[148:149], v[132:133]
	v_mov_b32_e32 v34, v139
	v_add_f32_e32 v33, v131, v33
	v_add_f32_e32 v33, v130, v33
	ds_bpermute_b32 v130, v101, v33
	v_pk_mul_f32 v[34:35], v[34:35], v[146:147]
	v_bfe_u32 v133, v65, 16, 1
	v_bfe_u32 v131, v35, 16, 1
	v_bfe_u32 v132, v34, 16, 1
	s_waitcnt lgkmcnt(0)
	v_add_f32_e32 v33, v33, v130
	ds_bpermute_b32 v130, v102, v33
	v_add3_u32 v65, v65, v133, s52
	v_add3_u32 v34, v34, v132, s52
	v_add3_u32 v35, v35, v131, s52
	v_bfe_u32 v131, v140, 16, 1
	s_waitcnt lgkmcnt(0)
	v_add_f32_e32 v33, v33, v130
	ds_bpermute_b32 v130, v103, v33
	v_bfe_u32 v132, v141, 16, 1
	v_bfe_u32 v133, v136, 16, 1
	v_add3_u32 v133, v136, v133, s52
	v_add3_u32 v132, v141, v132, s52
	s_waitcnt lgkmcnt(0)
	v_add_f32_e32 v33, v33, v130
	ds_bpermute_b32 v130, v104, v33
	v_add3_u32 v131, v140, v131, s52
	v_bfe_u32 v138, v64, 16, 1
	v_lshrrev_b32_e32 v136, 16, v131
	v_lshrrev_b32_e32 v131, 16, v132
	s_waitcnt lgkmcnt(0)
	v_add_f32_e32 v33, v33, v130
	ds_bpermute_b32 v130, v105, v33
	v_lshrrev_b32_e32 v132, 16, v133
	v_add3_u32 v64, v64, v138, s52
	v_bfe_u32 v138, v137, 16, 1
	v_and_or_b32 v132, v34, s53, v132
	s_waitcnt lgkmcnt(0)
	v_add_f32_e32 v33, v33, v130
	ds_bpermute_b32 v130, v106, v33
	v_add3_u32 v137, v137, v138, s52
	v_lshrrev_b32_e32 v133, 16, v137
	v_and_or_b32 v131, v65, s53, v131
	v_and_or_b32 v133, v35, s53, v133
	s_waitcnt lgkmcnt(0)
	v_add_f32_e32 v33, v33, v130
	v_fmamk_f32 v33, v33, 0x3b000000, v123
	v_mul_f32_e32 v34, 0x4f800000, v33
	v_cmp_gt_f32_e32 vcc, s45, v33
	v_and_or_b32 v130, v64, s53, v136
	s_nop 0
	v_cndmask_b32_e32 v33, v33, v34, vcc
	v_sqrt_f32_e32 v137, v33
	v_lshl_add_u64 v[34:35], s[40:41], 0, v[58:59]
	v_lshlrev_b64 v[34:35], 11, v[34:35]
	v_lshl_add_u64 v[34:35], v[62:63], 0, v[34:35]
	v_add_u32_e32 v64, -1, v137
	v_fma_f32 v65, -v64, v137, v33
	v_cmp_ge_f32_e64 s[0:1], 0, v65
	v_add_u32_e32 v65, 1, v137
	v_fma_f32 v136, -v65, v137, v33
	v_cndmask_b32_e64 v64, v137, v64, s[0:1]
	v_cmp_lt_f32_e64 s[0:1], 0, v136
	global_store_dwordx4 v[34:35], v[130:133], off offset:1024
	s_nop 0
	v_cndmask_b32_e64 v64, v64, v65, s[0:1]
	v_mul_f32_e32 v65, 0x37800000, v64
	v_cndmask_b32_e32 v64, v64, v65, vcc
	v_cmp_class_f32_e32 vcc, v33, v124
	s_nop 1
	v_cndmask_b32_e32 v33, v64, v33, vcc
	v_div_scale_f32 v64, s[0:1], v33, v33, 1.0
	v_rcp_f32_e32 v65, v64
	s_nop 0
	v_fma_f32 v34, -v64, v65, 1.0
	v_fmac_f32_e32 v65, v34, v65
	v_div_scale_f32 v34, vcc, 1.0, v33, 1.0
	v_mul_f32_e32 v35, v34, v65
	v_fma_f32 v130, -v64, v35, v34
	v_fmac_f32_e32 v35, v130, v65
	v_fma_f32 v34, -v64, v35, v34
	v_div_fmas_f32 v34, v34, v65, v35
	v_div_fixup_f32 v34, v34, v33, 1.0
	v_pk_mul_f32 v[64:65], v[128:129], v[34:35] op_sel_hi:[1,0]
	v_pk_mul_f32 v[130:131], v[144:145], v[34:35] op_sel_hi:[1,0]
	v_pk_fma_f32 v[64:65], v[8:9], v[64:65], v[12:13]
	v_pk_fma_f32 v[130:131], v[0:1], v[130:131], v[4:5]
	v_mul_f32_e32 v33, 0xbfb8aa3b, v64
	v_exp_f32_e32 v33, v33
	v_mul_f32_e32 v132, 0xbfb8aa3b, v130
	v_exp_f32_e32 v133, v132
	v_pk_mul_f32 v[128:129], v[142:143], v[34:35] op_sel_hi:[1,0]
	v_add_f32_e32 v33, 1.0, v33
	v_rcp_f32_e32 v132, v33
	v_add_f32_e32 v33, 1.0, v133
	v_mul_f32_e32 v133, 0xbfb8aa3b, v65
	v_pk_mul_f32 v[34:35], v[134:135], v[34:35] op_sel_hi:[1,0]
	v_exp_f32_e32 v133, v133
	v_mul_f32_e32 v134, 0xbfb8aa3b, v131
	v_exp_f32_e32 v135, v134
	v_pk_fma_f32 v[128:129], v[10:11], v[128:129], v[14:15]
	v_pk_fma_f32 v[34:35], v[2:3], v[34:35], v[6:7]
	v_rcp_f32_e32 v134, v33
	v_add_f32_e32 v33, 1.0, v133
	v_mul_f32_e32 v133, 0xbfb8aa3b, v128
	v_rcp_f32_e32 v136, v33
	v_add_f32_e32 v33, 1.0, v135
	v_exp_f32_e32 v133, v133
	v_mul_f32_e32 v135, 0xbfb8aa3b, v34
	v_exp_f32_e32 v135, v135
	v_rcp_f32_e32 v138, v33
	v_add_f32_e32 v33, 1.0, v133
	v_rcp_f32_e32 v133, v33
	v_add_f32_e32 v33, 1.0, v135
	v_mul_f32_e32 v135, 0xbfb8aa3b, v129
	v_exp_f32_e32 v137, v135
	v_mul_f32_e32 v135, 0xbfb8aa3b, v35
	v_exp_f32_e32 v139, v135
	v_rcp_f32_e32 v135, v33
	v_add_f32_e32 v33, 1.0, v137
	v_rcp_f32_e32 v137, v33
	v_add_f32_e32 v33, 1.0, v139
	v_rcp_f32_e32 v139, v33
	v_mov_b32_e32 v141, v128
	v_mov_b32_e32 v128, v65
	v_mov_b32_e32 v140, v64
	v_pk_mul_f32 v[64:65], v[128:129], v[136:137]
	v_mov_b32_e32 v129, v34
	v_mov_b32_e32 v34, v131
	v_mov_b32_e32 v128, v130
	v_pk_mul_f32 v[34:35], v[34:35], v[138:139]
	v_pk_mul_f32 v[132:133], v[140:141], v[132:133]
	v_pk_mul_f32 v[128:129], v[128:129], v[134:135]
	v_bfe_u32 v33, v35, 16, 1
	v_bfe_u32 v131, v65, 16, 1
	v_bfe_u32 v130, v34, 16, 1
	v_add3_u32 v65, v65, v131, s52
	v_add3_u32 v33, v35, v33, s52
	v_bfe_u32 v35, v132, 16, 1
	v_bfe_u32 v131, v128, 16, 1
	v_bfe_u32 v134, v64, 16, 1
	v_add3_u32 v34, v34, v130, s52
	v_bfe_u32 v130, v133, 16, 1
	v_add3_u32 v128, v128, v131, s52
	v_add3_u32 v35, v132, v35, s52
	v_add3_u32 v64, v64, v134, s52
	v_bfe_u32 v134, v129, 16, 1
	v_add3_u32 v130, v133, v130, s52
	v_lshrrev_b32_e32 v35, 16, v35
	v_lshrrev_b32_e32 v128, 16, v128
	v_add3_u32 v129, v129, v134, s52
	v_lshrrev_b32_e32 v132, 16, v130
	v_and_or_b32 v130, v34, s53, v128
	v_and_or_b32 v128, v64, s53, v35
	v_lshl_add_u64 v[34:35], s[40:41], 0, v[60:61]
	v_lshrrev_b32_e32 v129, 16, v129
	v_lshlrev_b64 v[34:35], 11, v[34:35]
	v_and_or_b32 v131, v33, s53, v129
	v_and_or_b32 v129, v65, s53, v132
	v_lshl_add_u64 v[34:35], v[62:63], 0, v[34:35]
	global_store_dwordx4 v[34:35], v[128:131], off offset:1024
	s_cbranch_scc0 .LBB0_484
